# GEMM k-loops: the three waits in front of each pre-MFMA barrier (vmcnt(8), lgkmcnt(0), lgkmcnt(0)) merged into one s_waitcnt vmcnt(8) lgkmcnt(0): two issue slots fewer before the reading group reaches
# speedup vs baseline: 1.0063x; 1.0063x over previous
.LBB0_145:
	s_add_u32 s27, s50, 0x100
	s_addc_u32 s56, s51, 0
	s_mov_b32 s57, -2
	s_waitcnt lgkmcnt(0)
	ds_read_b128 v[128:131], v188
	ds_read_b128 v[132:135], v188 offset:1024
	ds_read_b128 v[136:139], v188 offset:2048
	ds_read_b128 v[140:143], v188 offset:3072
	ds_read_b128 v[144:147], v189
	ds_read_b128 v[148:151], v189 offset:1024
	ds_read_b128 v[176:179], v189 offset:2048
	ds_read_b128 v[180:183], v189 offset:3072
	s_add_u32 s50, s48, 0x100
	s_addc_u32 s51, s49, 0
	s_cmp_eq_u32 s57, 28
	s_cselect_b32 s55, s21, s51
	s_cselect_b32 s54, s20, s50
	s_cselect_b32 s53, s23, s56
	s_cselect_b32 s52, s22, s27
	v_lshl_add_u64 v[184:185], s[48:49], 0, v[170:171]
	s_add_i32 m0, s60, 0xc000
	ds_read_b128 v[194:197], v190
	ds_read_b128 v[198:201], v190 offset:1024
	ds_read_b128 v[202:205], v190 offset:2048
	ds_read_b128 v[206:209], v190 offset:3072
	ds_read_b128 v[210:213], v190 offset:4096
	ds_read_b128 v[214:217], v190 offset:5120
	ds_read_b128 v[218:221], v190 offset:6144
	ds_read_b128 v[222:225], v190 offset:7168
	global_load_lds_dwordx4 v[184:185], off
	v_lshl_add_u64 v[184:185], s[48:49], 0, v[172:173]
	s_add_i32 m0, s60, 0xe000
	s_nop 0
	global_load_lds_dwordx4 v[184:185], off
	s_waitcnt vmcnt(8) lgkmcnt(0)
	s_setprio 1
	s_barrier
	v_mfma_f32_16x16x32_bf16 v[120:123], v[128:131], v[194:197], 0
	v_mfma_f32_16x16x32_bf16 v[124:127], v[136:139], v[194:197], 0
	v_mfma_f32_16x16x32_bf16 v[108:111], v[128:131], v[202:205], 0
	v_mfma_f32_16x16x32_bf16 v[104:107], v[136:139], v[202:205], 0
	v_mfma_f32_16x16x32_bf16 v[92:95], v[128:131], v[210:213], 0
	v_mfma_f32_16x16x32_bf16 v[88:91], v[136:139], v[210:213], 0
	v_mfma_f32_16x16x32_bf16 v[76:79], v[128:131], v[218:221], 0
	v_mfma_f32_16x16x32_bf16 v[72:75], v[136:139], v[218:221], 0
	v_mfma_f32_16x16x32_bf16 v[120:123], v[132:135], v[198:201], v[120:123]
	v_mfma_f32_16x16x32_bf16 v[124:127], v[140:143], v[198:201], v[124:127]
	v_mfma_f32_16x16x32_bf16 v[108:111], v[132:135], v[206:209], v[108:111]
	v_mfma_f32_16x16x32_bf16 v[104:107], v[140:143], v[206:209], v[104:107]
	v_mfma_f32_16x16x32_bf16 v[92:95], v[132:135], v[214:217], v[92:95]
	v_mfma_f32_16x16x32_bf16 v[88:91], v[140:143], v[214:217], v[88:91]
	v_mfma_f32_16x16x32_bf16 v[76:79], v[132:135], v[222:225], v[76:79]
	v_mfma_f32_16x16x32_bf16 v[72:75], v[140:143], v[222:225], v[72:75]
	s_setprio 0
	s_setprio 1
	v_mfma_f32_16x16x32_bf16 v[112:115], v[144:147], v[194:197], 0
	v_mfma_f32_16x16x32_bf16 v[116:119], v[176:179], v[194:197], 0
	v_mfma_f32_16x16x32_bf16 v[100:103], v[144:147], v[202:205], 0
	v_mfma_f32_16x16x32_bf16 v[96:99], v[176:179], v[202:205], 0
	v_mfma_f32_16x16x32_bf16 v[84:87], v[144:147], v[210:213], 0
	v_mfma_f32_16x16x32_bf16 v[80:83], v[176:179], v[210:213], 0
	v_mfma_f32_16x16x32_bf16 v[68:71], v[144:147], v[218:221], 0
	v_mfma_f32_16x16x32_bf16 v[64:67], v[176:179], v[218:221], 0
	v_mfma_f32_16x16x32_bf16 v[112:115], v[148:151], v[198:201], v[112:115]
	v_mfma_f32_16x16x32_bf16 v[116:119], v[180:183], v[198:201], v[116:119]
	v_mfma_f32_16x16x32_bf16 v[100:103], v[148:151], v[206:209], v[100:103]
	v_mfma_f32_16x16x32_bf16 v[96:99], v[180:183], v[206:209], v[96:99]
	v_mfma_f32_16x16x32_bf16 v[84:87], v[148:151], v[214:217], v[84:87]
	v_mfma_f32_16x16x32_bf16 v[80:83], v[180:183], v[214:217], v[80:83]
	v_mfma_f32_16x16x32_bf16 v[68:71], v[148:151], v[222:225], v[68:71]
	v_mfma_f32_16x16x32_bf16 v[64:67], v[180:183], v[222:225], v[64:67]
	s_barrier
	s_setprio 0
	s_add_i32 s48, s71, s3
	v_lshl_add_u64 v[184:185], s[52:53], 0, v[154:155]
	s_mov_b32 m0, s48
	ds_read_b128 v[194:197], v190 offset:16384
	ds_read_b128 v[198:201], v190 offset:17408
	ds_read_b128 v[202:205], v190 offset:18432
	ds_read_b128 v[206:209], v190 offset:19456
	ds_read_b128 v[210:213], v190 offset:20480
	ds_read_b128 v[214:217], v190 offset:21504
	ds_read_b128 v[218:221], v190 offset:22528
	ds_read_b128 v[222:225], v190 offset:23552
	global_load_lds_dwordx4 v[184:185], off
	s_add_i32 m0, s48, 0x2000
	s_add_u32 s48, s52, 0x80000
	v_lshl_add_u64 v[226:227], s[52:53], 0, v[158:159]
	s_addc_u32 s49, s53, 0
	s_add_i32 s58, s72, s3
	global_load_lds_dwordx4 v[226:227], off
	v_lshl_add_u64 v[228:229], s[48:49], 0, v[154:155]
	s_mov_b32 m0, s58
	v_lshl_add_u64 v[230:231], s[54:55], 0, v[156:157]
	global_load_lds_dwordx4 v[228:229], off
	v_lshl_add_u64 v[228:229], s[48:49], 0, v[158:159]
	s_add_i32 m0, s58, 0x2000
	s_nop 0
	global_load_lds_dwordx4 v[228:229], off
	v_lshl_add_u64 v[228:229], s[54:55], 0, v[152:153]
	s_mov_b32 m0, s60
	s_nop 0
	global_load_lds_dwordx4 v[228:229], off
	s_mov_b32 m0, s61
	s_nop 0
	global_load_lds_dwordx4 v[230:231], off
	s_waitcnt vmcnt(8) lgkmcnt(0)
	s_setprio 1
	s_barrier
	v_mfma_f32_16x16x32_bf16 v[60:63], v[128:131], v[194:197], 0
	v_mfma_f32_16x16x32_bf16 v[56:59], v[136:139], v[194:197], 0
	v_mfma_f32_16x16x32_bf16 v[44:47], v[128:131], v[202:205], 0
	v_mfma_f32_16x16x32_bf16 v[40:43], v[136:139], v[202:205], 0
	v_mfma_f32_16x16x32_bf16 v[28:31], v[128:131], v[210:213], 0
	v_mfma_f32_16x16x32_bf16 v[24:27], v[136:139], v[210:213], 0
	v_mfma_f32_16x16x32_bf16 v[12:15], v[128:131], v[218:221], 0
	v_mfma_f32_16x16x32_bf16 v[8:11], v[136:139], v[218:221], 0
	v_mfma_f32_16x16x32_bf16 v[60:63], v[132:135], v[198:201], v[60:63]
	v_mfma_f32_16x16x32_bf16 v[56:59], v[140:143], v[198:201], v[56:59]
	v_mfma_f32_16x16x32_bf16 v[44:47], v[132:135], v[206:209], v[44:47]
	v_mfma_f32_16x16x32_bf16 v[40:43], v[140:143], v[206:209], v[40:43]
	v_mfma_f32_16x16x32_bf16 v[28:31], v[132:135], v[214:217], v[28:31]
	v_mfma_f32_16x16x32_bf16 v[24:27], v[140:143], v[214:217], v[24:27]
	v_mfma_f32_16x16x32_bf16 v[12:15], v[132:135], v[222:225], v[12:15]
	v_mfma_f32_16x16x32_bf16 v[8:11], v[140:143], v[222:225], v[8:11]
	s_setprio 0
	s_setprio 1
	v_mfma_f32_16x16x32_bf16 v[52:55], v[144:147], v[194:197], 0
	v_mfma_f32_16x16x32_bf16 v[48:51], v[176:179], v[194:197], 0
	v_mfma_f32_16x16x32_bf16 v[36:39], v[144:147], v[202:205], 0
	v_mfma_f32_16x16x32_bf16 v[32:35], v[176:179], v[202:205], 0
	v_mfma_f32_16x16x32_bf16 v[20:23], v[144:147], v[210:213], 0
	v_mfma_f32_16x16x32_bf16 v[16:19], v[176:179], v[210:213], 0
	v_mfma_f32_16x16x32_bf16 v[4:7], v[144:147], v[218:221], 0
	v_mfma_f32_16x16x32_bf16 v[0:3], v[176:179], v[218:221], 0
	v_mfma_f32_16x16x32_bf16 v[52:55], v[148:151], v[198:201], v[52:55]
	v_mfma_f32_16x16x32_bf16 v[48:51], v[180:183], v[198:201], v[48:51]
	v_mfma_f32_16x16x32_bf16 v[36:39], v[148:151], v[206:209], v[36:39]
	v_mfma_f32_16x16x32_bf16 v[32:35], v[180:183], v[206:209], v[32:35]
	v_mfma_f32_16x16x32_bf16 v[20:23], v[148:151], v[214:217], v[20:23]
	v_mfma_f32_16x16x32_bf16 v[16:19], v[180:183], v[214:217], v[16:19]
	v_mfma_f32_16x16x32_bf16 v[4:7], v[148:151], v[222:225], v[4:7]
	v_mfma_f32_16x16x32_bf16 v[0:3], v[180:183], v[222:225], v[0:3]
	s_barrier
	s_setprio 0
	s_branch .Lpeel_mid_p1
	s_nop 0
	s_nop 0
	s_nop 0
	s_nop 0
.LBB0_146:
	ds_read_b128 v[128:131], v188
	ds_read_b128 v[132:135], v188 offset:1024
	ds_read_b128 v[136:139], v188 offset:2048
	ds_read_b128 v[140:143], v188 offset:3072
	ds_read_b128 v[144:147], v189
	ds_read_b128 v[148:151], v189 offset:1024
	ds_read_b128 v[176:179], v189 offset:2048
	ds_read_b128 v[180:183], v189 offset:3072
	s_add_u32 s50, s48, 0x100
	s_addc_u32 s51, s49, 0
	s_cmp_eq_u32 s57, 28
	s_cselect_b32 s55, s21, s51
	s_cselect_b32 s54, s20, s50
	s_cselect_b32 s53, s23, s56
	s_cselect_b32 s52, s22, s27
	v_lshl_add_u64 v[184:185], s[48:49], 0, v[170:171]
	s_add_i32 m0, s60, 0xc000
	ds_read_b128 v[194:197], v190
	ds_read_b128 v[198:201], v190 offset:1024
	ds_read_b128 v[202:205], v190 offset:2048
	ds_read_b128 v[206:209], v190 offset:3072
	ds_read_b128 v[210:213], v190 offset:4096
	ds_read_b128 v[214:217], v190 offset:5120
	ds_read_b128 v[218:221], v190 offset:6144
	ds_read_b128 v[222:225], v190 offset:7168
	global_load_lds_dwordx4 v[184:185], off
	v_lshl_add_u64 v[184:185], s[48:49], 0, v[172:173]
	s_add_i32 m0, s60, 0xe000
	s_nop 0
	global_load_lds_dwordx4 v[184:185], off
	s_waitcnt vmcnt(8) lgkmcnt(0)
	s_setprio 1
	s_barrier
	v_mfma_f32_16x16x32_bf16 v[120:123], v[128:131], v[194:197], v[120:123]
	v_mfma_f32_16x16x32_bf16 v[124:127], v[136:139], v[194:197], v[124:127]
	v_mfma_f32_16x16x32_bf16 v[108:111], v[128:131], v[202:205], v[108:111]
	v_mfma_f32_16x16x32_bf16 v[104:107], v[136:139], v[202:205], v[104:107]
	v_mfma_f32_16x16x32_bf16 v[92:95], v[128:131], v[210:213], v[92:95]
	v_mfma_f32_16x16x32_bf16 v[88:91], v[136:139], v[210:213], v[88:91]
	v_mfma_f32_16x16x32_bf16 v[76:79], v[128:131], v[218:221], v[76:79]
	v_mfma_f32_16x16x32_bf16 v[72:75], v[136:139], v[218:221], v[72:75]
	v_mfma_f32_16x16x32_bf16 v[120:123], v[132:135], v[198:201], v[120:123]
	v_mfma_f32_16x16x32_bf16 v[124:127], v[140:143], v[198:201], v[124:127]
	v_mfma_f32_16x16x32_bf16 v[108:111], v[132:135], v[206:209], v[108:111]
	v_mfma_f32_16x16x32_bf16 v[104:107], v[140:143], v[206:209], v[104:107]
	v_mfma_f32_16x16x32_bf16 v[92:95], v[132:135], v[214:217], v[92:95]
	v_mfma_f32_16x16x32_bf16 v[88:91], v[140:143], v[214:217], v[88:91]
	v_mfma_f32_16x16x32_bf16 v[76:79], v[132:135], v[222:225], v[76:79]
	v_mfma_f32_16x16x32_bf16 v[72:75], v[140:143], v[222:225], v[72:75]
	s_setprio 0
	s_setprio 1
	v_mfma_f32_16x16x32_bf16 v[112:115], v[144:147], v[194:197], v[112:115]
	v_mfma_f32_16x16x32_bf16 v[116:119], v[176:179], v[194:197], v[116:119]
	v_mfma_f32_16x16x32_bf16 v[100:103], v[144:147], v[202:205], v[100:103]
	v_mfma_f32_16x16x32_bf16 v[96:99], v[176:179], v[202:205], v[96:99]
	v_mfma_f32_16x16x32_bf16 v[84:87], v[144:147], v[210:213], v[84:87]
	v_mfma_f32_16x16x32_bf16 v[80:83], v[176:179], v[210:213], v[80:83]
	v_mfma_f32_16x16x32_bf16 v[68:71], v[144:147], v[218:221], v[68:71]
	v_mfma_f32_16x16x32_bf16 v[64:67], v[176:179], v[218:221], v[64:67]
	v_mfma_f32_16x16x32_bf16 v[112:115], v[148:151], v[198:201], v[112:115]
	v_mfma_f32_16x16x32_bf16 v[116:119], v[180:183], v[198:201], v[116:119]
	v_mfma_f32_16x16x32_bf16 v[100:103], v[148:151], v[206:209], v[100:103]
	v_mfma_f32_16x16x32_bf16 v[96:99], v[180:183], v[206:209], v[96:99]
	v_mfma_f32_16x16x32_bf16 v[84:87], v[148:151], v[214:217], v[84:87]
	v_mfma_f32_16x16x32_bf16 v[80:83], v[180:183], v[214:217], v[80:83]
	v_mfma_f32_16x16x32_bf16 v[68:71], v[148:151], v[222:225], v[68:71]
	v_mfma_f32_16x16x32_bf16 v[64:67], v[180:183], v[222:225], v[64:67]
	s_barrier
	s_setprio 0
	s_add_i32 s48, s71, s3
	v_lshl_add_u64 v[184:185], s[52:53], 0, v[154:155]
	s_mov_b32 m0, s48
	ds_read_b128 v[194:197], v190 offset:16384
	ds_read_b128 v[198:201], v190 offset:17408
	ds_read_b128 v[202:205], v190 offset:18432
	ds_read_b128 v[206:209], v190 offset:19456
	ds_read_b128 v[210:213], v190 offset:20480
	ds_read_b128 v[214:217], v190 offset:21504
	ds_read_b128 v[218:221], v190 offset:22528
	ds_read_b128 v[222:225], v190 offset:23552
	global_load_lds_dwordx4 v[184:185], off
	s_add_i32 m0, s48, 0x2000
	s_add_u32 s48, s52, 0x80000
	v_lshl_add_u64 v[226:227], s[52:53], 0, v[158:159]
	s_addc_u32 s49, s53, 0
	s_add_i32 s58, s72, s3
	global_load_lds_dwordx4 v[226:227], off
	v_lshl_add_u64 v[228:229], s[48:49], 0, v[154:155]
	s_mov_b32 m0, s58
	v_lshl_add_u64 v[230:231], s[54:55], 0, v[156:157]
	global_load_lds_dwordx4 v[228:229], off
	v_lshl_add_u64 v[228:229], s[48:49], 0, v[158:159]
	s_add_i32 m0, s58, 0x2000
	s_nop 0
	global_load_lds_dwordx4 v[228:229], off
	v_lshl_add_u64 v[228:229], s[54:55], 0, v[152:153]
	s_mov_b32 m0, s60
	s_nop 0
	global_load_lds_dwordx4 v[228:229], off
	s_mov_b32 m0, s61
	s_nop 0
	global_load_lds_dwordx4 v[230:231], off
	s_waitcnt vmcnt(8) lgkmcnt(0)
	s_setprio 1
	s_barrier
	v_mfma_f32_16x16x32_bf16 v[60:63], v[128:131], v[194:197], v[60:63]
	v_mfma_f32_16x16x32_bf16 v[56:59], v[136:139], v[194:197], v[56:59]
	v_mfma_f32_16x16x32_bf16 v[44:47], v[128:131], v[202:205], v[44:47]
	v_mfma_f32_16x16x32_bf16 v[40:43], v[136:139], v[202:205], v[40:43]
	v_mfma_f32_16x16x32_bf16 v[28:31], v[128:131], v[210:213], v[28:31]
	v_mfma_f32_16x16x32_bf16 v[24:27], v[136:139], v[210:213], v[24:27]
	v_mfma_f32_16x16x32_bf16 v[12:15], v[128:131], v[218:221], v[12:15]
	v_mfma_f32_16x16x32_bf16 v[8:11], v[136:139], v[218:221], v[8:11]
	v_mfma_f32_16x16x32_bf16 v[60:63], v[132:135], v[198:201], v[60:63]
	v_mfma_f32_16x16x32_bf16 v[56:59], v[140:143], v[198:201], v[56:59]
	v_mfma_f32_16x16x32_bf16 v[44:47], v[132:135], v[206:209], v[44:47]
	v_mfma_f32_16x16x32_bf16 v[40:43], v[140:143], v[206:209], v[40:43]
	v_mfma_f32_16x16x32_bf16 v[28:31], v[132:135], v[214:217], v[28:31]
	v_mfma_f32_16x16x32_bf16 v[24:27], v[140:143], v[214:217], v[24:27]
	v_mfma_f32_16x16x32_bf16 v[12:15], v[132:135], v[222:225], v[12:15]
	v_mfma_f32_16x16x32_bf16 v[8:11], v[140:143], v[222:225], v[8:11]
	s_setprio 0
	s_setprio 1
	v_mfma_f32_16x16x32_bf16 v[52:55], v[144:147], v[194:197], v[52:55]
	v_mfma_f32_16x16x32_bf16 v[48:51], v[176:179], v[194:197], v[48:51]
	v_mfma_f32_16x16x32_bf16 v[36:39], v[144:147], v[202:205], v[36:39]
	v_mfma_f32_16x16x32_bf16 v[32:35], v[176:179], v[202:205], v[32:35]
	v_mfma_f32_16x16x32_bf16 v[20:23], v[144:147], v[210:213], v[20:23]
	v_mfma_f32_16x16x32_bf16 v[16:19], v[176:179], v[210:213], v[16:19]
	v_mfma_f32_16x16x32_bf16 v[4:7], v[144:147], v[218:221], v[4:7]
	v_mfma_f32_16x16x32_bf16 v[0:3], v[176:179], v[218:221], v[0:3]
	v_mfma_f32_16x16x32_bf16 v[52:55], v[148:151], v[198:201], v[52:55]
	v_mfma_f32_16x16x32_bf16 v[48:51], v[180:183], v[198:201], v[48:51]
	v_mfma_f32_16x16x32_bf16 v[36:39], v[148:151], v[206:209], v[36:39]
	v_mfma_f32_16x16x32_bf16 v[32:35], v[180:183], v[206:209], v[32:35]
	v_mfma_f32_16x16x32_bf16 v[20:23], v[148:151], v[214:217], v[20:23]
	v_mfma_f32_16x16x32_bf16 v[16:19], v[180:183], v[214:217], v[16:19]
	v_mfma_f32_16x16x32_bf16 v[4:7], v[148:151], v[222:225], v[4:7]
	v_mfma_f32_16x16x32_bf16 v[0:3], v[180:183], v[222:225], v[0:3]
	s_barrier
	s_setprio 0
.Lpeel_mid_p1:
	s_add_i32 s58, 0, 0x18000
	s_add_i32 s59, 0, 0x1c000
	v_add_u32_e32 v140, s58, v186
	v_add_u32_e32 v160, s59, v186
	ds_read_b128 v[128:131], v140
	ds_read_b128 v[132:135], v140 offset:1024
	ds_read_b128 v[136:139], v140 offset:2048
	ds_read_b128 v[140:143], v140 offset:3072
	ds_read_b128 v[144:147], v160
	ds_read_b128 v[148:151], v160 offset:1024
	ds_read_b128 v[176:179], v160 offset:2048
	ds_read_b128 v[180:183], v160 offset:3072
	s_add_u32 s48, s54, 0xa0000
	s_addc_u32 s49, s55, 0
	s_mov_b32 m0, s62
	v_lshl_add_u64 v[232:233], s[48:49], 0, v[152:153]
	ds_read_b128 v[194:197], v190 offset:32768
	ds_read_b128 v[198:201], v190 offset:33792
	ds_read_b128 v[202:205], v190 offset:34816
	ds_read_b128 v[206:209], v190 offset:35840
	ds_read_b128 v[210:213], v190 offset:36864
	ds_read_b128 v[214:217], v190 offset:37888
	ds_read_b128 v[218:221], v190 offset:38912
	ds_read_b128 v[222:225], v190 offset:39936
	global_load_lds_dwordx4 v[232:233], off
	v_lshl_add_u64 v[232:233], s[48:49], 0, v[156:157]
	s_mov_b32 m0, s63
	s_nop 0
	global_load_lds_dwordx4 v[232:233], off
	s_waitcnt vmcnt(8) lgkmcnt(0)
	s_setprio 1
	s_barrier
	v_mfma_f32_16x16x32_bf16 v[120:123], v[128:131], v[194:197], v[120:123]
	v_mfma_f32_16x16x32_bf16 v[124:127], v[136:139], v[194:197], v[124:127]
	v_mfma_f32_16x16x32_bf16 v[108:111], v[128:131], v[202:205], v[108:111]
	v_mfma_f32_16x16x32_bf16 v[104:107], v[136:139], v[202:205], v[104:107]
	v_mfma_f32_16x16x32_bf16 v[92:95], v[128:131], v[210:213], v[92:95]
	v_mfma_f32_16x16x32_bf16 v[88:91], v[136:139], v[210:213], v[88:91]
	v_mfma_f32_16x16x32_bf16 v[76:79], v[128:131], v[218:221], v[76:79]
	v_mfma_f32_16x16x32_bf16 v[72:75], v[136:139], v[218:221], v[72:75]
	v_mfma_f32_16x16x32_bf16 v[120:123], v[132:135], v[198:201], v[120:123]
	v_mfma_f32_16x16x32_bf16 v[124:127], v[140:143], v[198:201], v[124:127]
	v_mfma_f32_16x16x32_bf16 v[108:111], v[132:135], v[206:209], v[108:111]
	v_mfma_f32_16x16x32_bf16 v[104:107], v[140:143], v[206:209], v[104:107]
	v_mfma_f32_16x16x32_bf16 v[92:95], v[132:135], v[214:217], v[92:95]
	v_mfma_f32_16x16x32_bf16 v[88:91], v[140:143], v[214:217], v[88:91]
	v_mfma_f32_16x16x32_bf16 v[76:79], v[132:135], v[222:225], v[76:79]
	v_mfma_f32_16x16x32_bf16 v[72:75], v[140:143], v[222:225], v[72:75]
	s_setprio 0
	s_setprio 1
	v_mfma_f32_16x16x32_bf16 v[112:115], v[144:147], v[194:197], v[112:115]
	v_mfma_f32_16x16x32_bf16 v[116:119], v[176:179], v[194:197], v[116:119]
	v_mfma_f32_16x16x32_bf16 v[100:103], v[144:147], v[202:205], v[100:103]
	v_mfma_f32_16x16x32_bf16 v[96:99], v[176:179], v[202:205], v[96:99]
	v_mfma_f32_16x16x32_bf16 v[84:87], v[144:147], v[210:213], v[84:87]
	v_mfma_f32_16x16x32_bf16 v[80:83], v[176:179], v[210:213], v[80:83]
	v_mfma_f32_16x16x32_bf16 v[68:71], v[144:147], v[218:221], v[68:71]
	v_mfma_f32_16x16x32_bf16 v[64:67], v[176:179], v[218:221], v[64:67]
	v_mfma_f32_16x16x32_bf16 v[112:115], v[148:151], v[198:201], v[112:115]
	v_mfma_f32_16x16x32_bf16 v[116:119], v[180:183], v[198:201], v[116:119]
	v_mfma_f32_16x16x32_bf16 v[100:103], v[148:151], v[206:209], v[100:103]
	v_mfma_f32_16x16x32_bf16 v[96:99], v[180:183], v[206:209], v[96:99]
	v_mfma_f32_16x16x32_bf16 v[84:87], v[148:151], v[214:217], v[84:87]
	v_mfma_f32_16x16x32_bf16 v[80:83], v[180:183], v[214:217], v[80:83]
	v_mfma_f32_16x16x32_bf16 v[68:71], v[148:151], v[222:225], v[68:71]
	v_mfma_f32_16x16x32_bf16 v[64:67], v[180:183], v[222:225], v[64:67]
	s_barrier
	s_setprio 0
	s_add_i32 s48, s58, s3
	v_lshl_add_u64 v[184:185], v[184:185], 0, s[14:15]
	s_mov_b32 m0, s48
	ds_read_b128 v[194:197], v190 offset:49152
	ds_read_b128 v[198:201], v190 offset:50176
	ds_read_b128 v[202:205], v190 offset:51200
	ds_read_b128 v[206:209], v190 offset:52224
	ds_read_b128 v[210:213], v190 offset:53248
	ds_read_b128 v[214:217], v190 offset:54272
	ds_read_b128 v[218:221], v190 offset:55296
	ds_read_b128 v[222:225], v190 offset:56320
	global_load_lds_dwordx4 v[184:185], off
	s_add_i32 m0, s48, 0x2000
	s_add_u32 s48, s52, 0x80080
	v_lshl_add_u64 v[184:185], v[226:227], 0, s[14:15]
	s_addc_u32 s49, s53, 0
	s_add_i32 s52, s59, s3
	global_load_lds_dwordx4 v[184:185], off
	v_lshl_add_u64 v[184:185], s[48:49], 0, v[154:155]
	s_mov_b32 m0, s52
	s_nop 0
	global_load_lds_dwordx4 v[184:185], off
	v_lshl_add_u64 v[184:185], s[48:49], 0, v[158:159]
	s_add_i32 m0, s52, 0x2000
	s_nop 0
	global_load_lds_dwordx4 v[184:185], off
	v_lshl_add_u64 v[184:185], v[228:229], 0, s[14:15]
	s_mov_b32 m0, s66
	s_nop 0
	global_load_lds_dwordx4 v[184:185], off
	v_lshl_add_u64 v[184:185], v[230:231], 0, s[14:15]
	s_mov_b32 m0, s67
	s_nop 0
	global_load_lds_dwordx4 v[184:185], off
	s_waitcnt vmcnt(8) lgkmcnt(0)
	s_setprio 1
	s_barrier
	v_mfma_f32_16x16x32_bf16 v[60:63], v[128:131], v[194:197], v[60:63]
	v_mfma_f32_16x16x32_bf16 v[56:59], v[136:139], v[194:197], v[56:59]
	v_mfma_f32_16x16x32_bf16 v[44:47], v[128:131], v[202:205], v[44:47]
	v_mfma_f32_16x16x32_bf16 v[40:43], v[136:139], v[202:205], v[40:43]
	v_mfma_f32_16x16x32_bf16 v[28:31], v[128:131], v[210:213], v[28:31]
	v_mfma_f32_16x16x32_bf16 v[24:27], v[136:139], v[210:213], v[24:27]
	v_mfma_f32_16x16x32_bf16 v[12:15], v[128:131], v[218:221], v[12:15]
	v_mfma_f32_16x16x32_bf16 v[8:11], v[136:139], v[218:221], v[8:11]
	v_mfma_f32_16x16x32_bf16 v[60:63], v[132:135], v[198:201], v[60:63]
	v_mfma_f32_16x16x32_bf16 v[56:59], v[140:143], v[198:201], v[56:59]
	v_mfma_f32_16x16x32_bf16 v[44:47], v[132:135], v[206:209], v[44:47]
	v_mfma_f32_16x16x32_bf16 v[40:43], v[140:143], v[206:209], v[40:43]
	v_mfma_f32_16x16x32_bf16 v[28:31], v[132:135], v[214:217], v[28:31]
	v_mfma_f32_16x16x32_bf16 v[24:27], v[140:143], v[214:217], v[24:27]
	v_mfma_f32_16x16x32_bf16 v[12:15], v[132:135], v[222:225], v[12:15]
	v_mfma_f32_16x16x32_bf16 v[8:11], v[140:143], v[222:225], v[8:11]
	s_setprio 0
	s_setprio 1
	v_mfma_f32_16x16x32_bf16 v[52:55], v[144:147], v[194:197], v[52:55]
	v_mfma_f32_16x16x32_bf16 v[48:51], v[176:179], v[194:197], v[48:51]
	v_mfma_f32_16x16x32_bf16 v[36:39], v[144:147], v[202:205], v[36:39]
	v_mfma_f32_16x16x32_bf16 v[32:35], v[176:179], v[202:205], v[32:35]
	s_add_i32 s57, s57, 2
	v_mfma_f32_16x16x32_bf16 v[20:23], v[144:147], v[210:213], v[20:23]
	s_add_u32 s27, s27, 0x100
	v_mfma_f32_16x16x32_bf16 v[16:19], v[176:179], v[210:213], v[16:19]
	s_addc_u32 s56, s56, 0
	v_mfma_f32_16x16x32_bf16 v[4:7], v[144:147], v[218:221], v[4:7]
	s_cmp_gt_u32 s57, 29
	v_mfma_f32_16x16x32_bf16 v[0:3], v[176:179], v[218:221], v[0:3]
	s_mov_b64 s[48:49], s[50:51]
	v_mfma_f32_16x16x32_bf16 v[52:55], v[148:151], v[198:201], v[52:55]
	v_mfma_f32_16x16x32_bf16 v[48:51], v[180:183], v[198:201], v[48:51]
	v_mfma_f32_16x16x32_bf16 v[36:39], v[148:151], v[206:209], v[36:39]
	v_mfma_f32_16x16x32_bf16 v[32:35], v[180:183], v[206:209], v[32:35]
	v_mfma_f32_16x16x32_bf16 v[20:23], v[148:151], v[214:217], v[20:23]
	v_mfma_f32_16x16x32_bf16 v[16:19], v[180:183], v[214:217], v[16:19]
	v_mfma_f32_16x16x32_bf16 v[4:7], v[148:151], v[222:225], v[4:7]
	v_mfma_f32_16x16x32_bf16 v[0:3], v[180:183], v[222:225], v[0:3]
	s_barrier
	s_setprio 0
	s_cbranch_scc0 .LBB0_146
	s_and_b64 vcc, exec, s[18:19]
	s_cbranch_vccz .LBB0_149
	s_barrier

.LBB0_250:
	ds_read_b128 v[148:151], v142
	ds_read_b128 v[152:155], v142 offset:1024
	ds_read_b128 v[156:159], v142 offset:2048
	ds_read_b128 v[160:163], v142 offset:3072
	ds_read_b128 v[164:167], v143
	ds_read_b128 v[168:171], v143 offset:1024
	ds_read_b128 v[176:179], v143 offset:2048
	ds_read_b128 v[180:183], v143 offset:3072
	s_add_i32 s20, s18, 0xf4f60080
	s_cmp_lg_u32 s52, 28
	s_cselect_b32 s20, s20, 0
	s_add_u32 s22, s2, s20
	s_addc_u32 s23, s3, 0
	s_add_u32 s20, s12, s20
	s_addc_u32 s21, s13, 0
	s_mov_b32 m0, s53
	v_lshl_add_u64 v[172:173], v[138:139], 0, s[18:19]
	ds_read_b128 v[188:191], v144
	ds_read_b128 v[192:195], v144 offset:1024
	ds_read_b128 v[196:199], v144 offset:2048
	ds_read_b128 v[200:203], v144 offset:3072
	ds_read_b128 v[204:207], v144 offset:4096
	ds_read_b128 v[208:211], v144 offset:5120
	ds_read_b128 v[212:215], v144 offset:6144
	ds_read_b128 v[216:219], v144 offset:7168
	global_load_lds_dwordx4 v[172:173], off
	v_lshl_add_u64 v[172:173], v[140:141], 0, s[18:19]
	s_mov_b32 m0, s54
	s_nop 0
	global_load_lds_dwordx4 v[172:173], off
	s_waitcnt vmcnt(8) lgkmcnt(0)
	s_setprio 1
	s_barrier
	v_mfma_f32_16x16x32_bf16 v[124:127], v[148:151], v[188:191], v[124:127]
	v_mfma_f32_16x16x32_bf16 v[120:123], v[156:159], v[188:191], v[120:123]
	v_mfma_f32_16x16x32_bf16 v[116:119], v[148:151], v[196:199], v[116:119]
	v_mfma_f32_16x16x32_bf16 v[112:115], v[156:159], v[196:199], v[112:115]
	v_mfma_f32_16x16x32_bf16 v[100:103], v[148:151], v[204:207], v[100:103]
	v_mfma_f32_16x16x32_bf16 v[96:99], v[156:159], v[204:207], v[96:99]
	v_mfma_f32_16x16x32_bf16 v[84:87], v[148:151], v[212:215], v[84:87]
	v_mfma_f32_16x16x32_bf16 v[80:83], v[156:159], v[212:215], v[80:83]
	v_mfma_f32_16x16x32_bf16 v[124:127], v[152:155], v[192:195], v[124:127]
	v_mfma_f32_16x16x32_bf16 v[120:123], v[160:163], v[192:195], v[120:123]
	v_mfma_f32_16x16x32_bf16 v[116:119], v[152:155], v[200:203], v[116:119]
	v_mfma_f32_16x16x32_bf16 v[112:115], v[160:163], v[200:203], v[112:115]
	v_mfma_f32_16x16x32_bf16 v[100:103], v[152:155], v[208:211], v[100:103]
	v_mfma_f32_16x16x32_bf16 v[96:99], v[160:163], v[208:211], v[96:99]
	v_mfma_f32_16x16x32_bf16 v[84:87], v[152:155], v[216:219], v[84:87]
	v_mfma_f32_16x16x32_bf16 v[80:83], v[160:163], v[216:219], v[80:83]
	s_setprio 0
	s_setprio 1
	v_mfma_f32_16x16x32_bf16 v[108:111], v[164:167], v[188:191], v[108:111]
	v_mfma_f32_16x16x32_bf16 v[104:107], v[176:179], v[188:191], v[104:107]
	v_mfma_f32_16x16x32_bf16 v[92:95], v[164:167], v[196:199], v[92:95]
	v_mfma_f32_16x16x32_bf16 v[88:91], v[176:179], v[196:199], v[88:91]
	v_mfma_f32_16x16x32_bf16 v[76:79], v[164:167], v[204:207], v[76:79]
	v_mfma_f32_16x16x32_bf16 v[72:75], v[176:179], v[204:207], v[72:75]
	v_mfma_f32_16x16x32_bf16 v[68:71], v[164:167], v[212:215], v[68:71]
	v_mfma_f32_16x16x32_bf16 v[64:67], v[176:179], v[212:215], v[64:67]
	v_mfma_f32_16x16x32_bf16 v[108:111], v[168:171], v[192:195], v[108:111]
	v_mfma_f32_16x16x32_bf16 v[104:107], v[180:183], v[192:195], v[104:107]
	v_mfma_f32_16x16x32_bf16 v[92:95], v[168:171], v[200:203], v[92:95]
	v_mfma_f32_16x16x32_bf16 v[88:91], v[180:183], v[200:203], v[88:91]
	v_mfma_f32_16x16x32_bf16 v[76:79], v[168:171], v[208:211], v[76:79]
	v_mfma_f32_16x16x32_bf16 v[72:75], v[180:183], v[208:211], v[72:75]
	v_mfma_f32_16x16x32_bf16 v[68:71], v[168:171], v[216:219], v[68:71]
	v_mfma_f32_16x16x32_bf16 v[64:67], v[180:183], v[216:219], v[64:67]
	s_barrier
	s_setprio 0
	s_mov_b32 m0, s55
	v_lshl_add_u64 v[172:173], s[20:21], 0, v[132:133]
	s_add_u32 s64, s20, 0x80000
	ds_read_b128 v[188:191], v144 offset:16384
	ds_read_b128 v[192:195], v144 offset:17408
	ds_read_b128 v[196:199], v144 offset:18432
	ds_read_b128 v[200:203], v144 offset:19456
	ds_read_b128 v[204:207], v144 offset:20480
	ds_read_b128 v[208:211], v144 offset:21504
	ds_read_b128 v[212:215], v144 offset:22528
	ds_read_b128 v[216:219], v144 offset:23552
	global_load_lds_dwordx4 v[172:173], off
	v_lshl_add_u64 v[184:185], s[20:21], 0, v[128:129]
	s_mov_b32 m0, s56
	s_addc_u32 s65, s21, 0
	global_load_lds_dwordx4 v[184:185], off
	v_lshl_add_u64 v[220:221], s[64:65], 0, v[132:133]
	s_mov_b32 m0, s57
	v_lshl_add_u64 v[222:223], s[22:23], 0, v[130:131]
	global_load_lds_dwordx4 v[220:221], off
	v_lshl_add_u64 v[220:221], s[64:65], 0, v[128:129]
	s_mov_b32 m0, s58
	s_nop 0
	global_load_lds_dwordx4 v[220:221], off
	v_lshl_add_u64 v[220:221], s[22:23], 0, v[134:135]
	s_mov_b32 m0, s1
	s_nop 0
	global_load_lds_dwordx4 v[220:221], off
	s_mov_b32 m0, s26
	s_nop 0
	global_load_lds_dwordx4 v[222:223], off
	s_waitcnt vmcnt(8) lgkmcnt(0)
	s_setprio 1
	s_barrier
	v_mfma_f32_16x16x32_bf16 v[60:63], v[148:151], v[188:191], v[60:63]
	v_mfma_f32_16x16x32_bf16 v[56:59], v[156:159], v[188:191], v[56:59]
	v_mfma_f32_16x16x32_bf16 v[52:55], v[148:151], v[196:199], v[52:55]
	v_mfma_f32_16x16x32_bf16 v[48:51], v[156:159], v[196:199], v[48:51]
	v_mfma_f32_16x16x32_bf16 v[36:39], v[148:151], v[204:207], v[36:39]
	v_mfma_f32_16x16x32_bf16 v[32:35], v[156:159], v[204:207], v[32:35]
	v_mfma_f32_16x16x32_bf16 v[20:23], v[148:151], v[212:215], v[20:23]
	v_mfma_f32_16x16x32_bf16 v[16:19], v[156:159], v[212:215], v[16:19]
	v_mfma_f32_16x16x32_bf16 v[60:63], v[152:155], v[192:195], v[60:63]
	v_mfma_f32_16x16x32_bf16 v[56:59], v[160:163], v[192:195], v[56:59]
	v_mfma_f32_16x16x32_bf16 v[52:55], v[152:155], v[200:203], v[52:55]
	v_mfma_f32_16x16x32_bf16 v[48:51], v[160:163], v[200:203], v[48:51]
	v_mfma_f32_16x16x32_bf16 v[36:39], v[152:155], v[208:211], v[36:39]
	v_mfma_f32_16x16x32_bf16 v[32:35], v[160:163], v[208:211], v[32:35]
	v_mfma_f32_16x16x32_bf16 v[20:23], v[152:155], v[216:219], v[20:23]
	v_mfma_f32_16x16x32_bf16 v[16:19], v[160:163], v[216:219], v[16:19]
	s_setprio 0
	s_setprio 1
	v_mfma_f32_16x16x32_bf16 v[44:47], v[164:167], v[188:191], v[44:47]
	v_mfma_f32_16x16x32_bf16 v[40:43], v[176:179], v[188:191], v[40:43]
	v_mfma_f32_16x16x32_bf16 v[28:31], v[164:167], v[196:199], v[28:31]
	v_mfma_f32_16x16x32_bf16 v[24:27], v[176:179], v[196:199], v[24:27]
	v_mfma_f32_16x16x32_bf16 v[12:15], v[164:167], v[204:207], v[12:15]
	v_mfma_f32_16x16x32_bf16 v[8:11], v[176:179], v[204:207], v[8:11]
	v_mfma_f32_16x16x32_bf16 v[4:7], v[164:167], v[212:215], v[4:7]
	v_mfma_f32_16x16x32_bf16 v[0:3], v[176:179], v[212:215], v[0:3]
	v_mfma_f32_16x16x32_bf16 v[44:47], v[168:171], v[192:195], v[44:47]
	v_mfma_f32_16x16x32_bf16 v[40:43], v[180:183], v[192:195], v[40:43]
	v_mfma_f32_16x16x32_bf16 v[28:31], v[168:171], v[200:203], v[28:31]
	v_mfma_f32_16x16x32_bf16 v[24:27], v[180:183], v[200:203], v[24:27]
	v_mfma_f32_16x16x32_bf16 v[12:15], v[168:171], v[208:211], v[12:15]
	v_mfma_f32_16x16x32_bf16 v[8:11], v[180:183], v[208:211], v[8:11]
	v_mfma_f32_16x16x32_bf16 v[4:7], v[168:171], v[216:219], v[4:7]
	v_mfma_f32_16x16x32_bf16 v[0:3], v[180:183], v[216:219], v[0:3]
	s_barrier
	s_setprio 0
	ds_read_b128 v[148:151], v145
	ds_read_b128 v[152:155], v145 offset:1024
	ds_read_b128 v[156:159], v145 offset:2048
	ds_read_b128 v[160:163], v145 offset:3072
	ds_read_b128 v[164:167], v146
	ds_read_b128 v[168:171], v146 offset:1024
	ds_read_b128 v[176:179], v146 offset:2048
	ds_read_b128 v[180:183], v146 offset:3072
	s_add_u32 s22, s22, 0xa0000
	s_addc_u32 s23, s23, 0
	s_mov_b32 m0, s27
	v_lshl_add_u64 v[224:225], s[22:23], 0, v[134:135]
	ds_read_b128 v[188:191], v144 offset:32768
	ds_read_b128 v[192:195], v144 offset:33792
	ds_read_b128 v[196:199], v144 offset:34816
	ds_read_b128 v[200:203], v144 offset:35840
	ds_read_b128 v[204:207], v144 offset:36864
	ds_read_b128 v[208:211], v144 offset:37888
	ds_read_b128 v[212:215], v144 offset:38912
	ds_read_b128 v[216:219], v144 offset:39936
	global_load_lds_dwordx4 v[224:225], off
	v_lshl_add_u64 v[224:225], s[22:23], 0, v[130:131]
	s_mov_b32 m0, s48
	s_nop 0
	global_load_lds_dwordx4 v[224:225], off
	s_waitcnt vmcnt(8) lgkmcnt(0)
	s_setprio 1
	s_barrier
	v_mfma_f32_16x16x32_bf16 v[124:127], v[148:151], v[188:191], v[124:127]
	v_mfma_f32_16x16x32_bf16 v[120:123], v[156:159], v[188:191], v[120:123]
	v_mfma_f32_16x16x32_bf16 v[116:119], v[148:151], v[196:199], v[116:119]
	v_mfma_f32_16x16x32_bf16 v[112:115], v[156:159], v[196:199], v[112:115]
	v_mfma_f32_16x16x32_bf16 v[100:103], v[148:151], v[204:207], v[100:103]
	v_mfma_f32_16x16x32_bf16 v[96:99], v[156:159], v[204:207], v[96:99]
	v_mfma_f32_16x16x32_bf16 v[84:87], v[148:151], v[212:215], v[84:87]
	v_mfma_f32_16x16x32_bf16 v[80:83], v[156:159], v[212:215], v[80:83]
	v_mfma_f32_16x16x32_bf16 v[124:127], v[152:155], v[192:195], v[124:127]
	v_mfma_f32_16x16x32_bf16 v[120:123], v[160:163], v[192:195], v[120:123]
	v_mfma_f32_16x16x32_bf16 v[116:119], v[152:155], v[200:203], v[116:119]
	v_mfma_f32_16x16x32_bf16 v[112:115], v[160:163], v[200:203], v[112:115]
	v_mfma_f32_16x16x32_bf16 v[100:103], v[152:155], v[208:211], v[100:103]
	v_mfma_f32_16x16x32_bf16 v[96:99], v[160:163], v[208:211], v[96:99]
	v_mfma_f32_16x16x32_bf16 v[84:87], v[152:155], v[216:219], v[84:87]
	v_mfma_f32_16x16x32_bf16 v[80:83], v[160:163], v[216:219], v[80:83]
	s_setprio 0
	s_setprio 1
	v_mfma_f32_16x16x32_bf16 v[108:111], v[164:167], v[188:191], v[108:111]
	v_mfma_f32_16x16x32_bf16 v[104:107], v[176:179], v[188:191], v[104:107]
	v_mfma_f32_16x16x32_bf16 v[92:95], v[164:167], v[196:199], v[92:95]
	v_mfma_f32_16x16x32_bf16 v[88:91], v[176:179], v[196:199], v[88:91]
	v_mfma_f32_16x16x32_bf16 v[76:79], v[164:167], v[204:207], v[76:79]
	v_mfma_f32_16x16x32_bf16 v[72:75], v[176:179], v[204:207], v[72:75]
	v_mfma_f32_16x16x32_bf16 v[68:71], v[164:167], v[212:215], v[68:71]
	v_mfma_f32_16x16x32_bf16 v[64:67], v[176:179], v[212:215], v[64:67]
	v_mfma_f32_16x16x32_bf16 v[108:111], v[168:171], v[192:195], v[108:111]
	v_mfma_f32_16x16x32_bf16 v[104:107], v[180:183], v[192:195], v[104:107]
	v_mfma_f32_16x16x32_bf16 v[92:95], v[168:171], v[200:203], v[92:95]
	v_mfma_f32_16x16x32_bf16 v[88:91], v[180:183], v[200:203], v[88:91]
	v_mfma_f32_16x16x32_bf16 v[76:79], v[168:171], v[208:211], v[76:79]
	v_mfma_f32_16x16x32_bf16 v[72:75], v[180:183], v[208:211], v[72:75]
	v_mfma_f32_16x16x32_bf16 v[68:71], v[168:171], v[216:219], v[68:71]
	v_mfma_f32_16x16x32_bf16 v[64:67], v[180:183], v[216:219], v[64:67]
	s_barrier
	s_setprio 0
	s_mov_b32 m0, s59
	v_lshl_add_u64 v[172:173], v[172:173], 0, s[14:15]
	s_add_u32 s20, s20, 0x80080
	ds_read_b128 v[188:191], v144 offset:49152
	ds_read_b128 v[192:195], v144 offset:50176
	ds_read_b128 v[196:199], v144 offset:51200
	ds_read_b128 v[200:203], v144 offset:52224
	ds_read_b128 v[204:207], v144 offset:53248
	ds_read_b128 v[208:211], v144 offset:54272
	ds_read_b128 v[212:215], v144 offset:55296
	ds_read_b128 v[216:219], v144 offset:56320
	global_load_lds_dwordx4 v[172:173], off
	v_lshl_add_u64 v[172:173], v[184:185], 0, s[14:15]
	s_mov_b32 m0, s60
	s_addc_u32 s21, s21, 0
	global_load_lds_dwordx4 v[172:173], off
	v_lshl_add_u64 v[172:173], s[20:21], 0, v[132:133]
	s_mov_b32 m0, s61
	s_nop 0
	global_load_lds_dwordx4 v[172:173], off
	v_lshl_add_u64 v[172:173], s[20:21], 0, v[128:129]
	s_mov_b32 m0, s62
	s_nop 0
	global_load_lds_dwordx4 v[172:173], off
	v_lshl_add_u64 v[172:173], v[220:221], 0, s[14:15]
	s_mov_b32 m0, s50
	s_nop 0
	global_load_lds_dwordx4 v[172:173], off
	v_lshl_add_u64 v[172:173], v[222:223], 0, s[14:15]
	s_mov_b32 m0, s51
	s_nop 0
	global_load_lds_dwordx4 v[172:173], off
	s_waitcnt vmcnt(8) lgkmcnt(0)
	s_setprio 1
	s_barrier
	v_mfma_f32_16x16x32_bf16 v[60:63], v[148:151], v[188:191], v[60:63]
	v_mfma_f32_16x16x32_bf16 v[56:59], v[156:159], v[188:191], v[56:59]
	v_mfma_f32_16x16x32_bf16 v[52:55], v[148:151], v[196:199], v[52:55]
	v_mfma_f32_16x16x32_bf16 v[48:51], v[156:159], v[196:199], v[48:51]
	v_mfma_f32_16x16x32_bf16 v[36:39], v[148:151], v[204:207], v[36:39]
	v_mfma_f32_16x16x32_bf16 v[32:35], v[156:159], v[204:207], v[32:35]
	v_mfma_f32_16x16x32_bf16 v[20:23], v[148:151], v[212:215], v[20:23]
	v_mfma_f32_16x16x32_bf16 v[16:19], v[156:159], v[212:215], v[16:19]
	v_mfma_f32_16x16x32_bf16 v[60:63], v[152:155], v[192:195], v[60:63]
	v_mfma_f32_16x16x32_bf16 v[56:59], v[160:163], v[192:195], v[56:59]
	v_mfma_f32_16x16x32_bf16 v[52:55], v[152:155], v[200:203], v[52:55]
	v_mfma_f32_16x16x32_bf16 v[48:51], v[160:163], v[200:203], v[48:51]
	v_mfma_f32_16x16x32_bf16 v[36:39], v[152:155], v[208:211], v[36:39]
	v_mfma_f32_16x16x32_bf16 v[32:35], v[160:163], v[208:211], v[32:35]
	v_mfma_f32_16x16x32_bf16 v[20:23], v[152:155], v[216:219], v[20:23]
	v_mfma_f32_16x16x32_bf16 v[16:19], v[160:163], v[216:219], v[16:19]
	s_setprio 0
	s_setprio 1
	v_mfma_f32_16x16x32_bf16 v[44:47], v[164:167], v[188:191], v[44:47]
	v_mfma_f32_16x16x32_bf16 v[40:43], v[176:179], v[188:191], v[40:43]
	v_mfma_f32_16x16x32_bf16 v[28:31], v[164:167], v[196:199], v[28:31]
	v_mfma_f32_16x16x32_bf16 v[24:27], v[176:179], v[196:199], v[24:27]
	v_mfma_f32_16x16x32_bf16 v[12:15], v[164:167], v[204:207], v[12:15]
	v_mfma_f32_16x16x32_bf16 v[8:11], v[176:179], v[204:207], v[8:11]
	v_mfma_f32_16x16x32_bf16 v[4:7], v[164:167], v[212:215], v[4:7]
	v_mfma_f32_16x16x32_bf16 v[0:3], v[176:179], v[212:215], v[0:3]
	v_mfma_f32_16x16x32_bf16 v[44:47], v[168:171], v[192:195], v[44:47]
	v_mfma_f32_16x16x32_bf16 v[40:43], v[180:183], v[192:195], v[40:43]
	v_mfma_f32_16x16x32_bf16 v[28:31], v[168:171], v[200:203], v[28:31]
	v_mfma_f32_16x16x32_bf16 v[24:27], v[180:183], v[200:203], v[24:27]
	v_mfma_f32_16x16x32_bf16 v[12:15], v[168:171], v[208:211], v[12:15]
	v_mfma_f32_16x16x32_bf16 v[8:11], v[180:183], v[208:211], v[8:11]
	v_mfma_f32_16x16x32_bf16 v[4:7], v[168:171], v[216:219], v[4:7]
	v_mfma_f32_16x16x32_bf16 v[0:3], v[180:183], v[216:219], v[0:3]
	s_barrier
	s_setprio 0
	s_add_i32 s52, s52, 2
	s_add_u32 s18, s18, 0x100
	s_addc_u32 s19, s19, 0
	s_cmp_gt_u32 s52, 29
	s_cbranch_scc0 .LBB0_250
	s_cmpk_lt_u32 s24, 0x100
	s_cbranch_scc0 .LBB0_253
	s_barrier

.LBB0_596:
	s_lshl_b32 s98, s56, 3
	s_add_i32 s98, s98, s2
	s_mul_i32 s98, s98, 3
	v_lshl_add_u32 v164, s56, 8, v172
	s_cmp_eq_u32 s87, 3
	v_mad_i64_i32 v[162:163], s[56:57], v164, s77, v[156:157]
	s_cselect_b64 s[62:63], -1, 0
	s_lshl_b32 s56, s2, 8
	s_ashr_i32 s57, s56, 31
	v_lshl_add_u64 v[2:3], s[56:57], 1, v[162:163]
	s_mov_b32 s7, s3
	v_lshl_add_u64 v[2:3], v[2:3], 0, s[6:7]
	v_lshl_add_u64 v[166:167], v[2:3], 0, v[160:161]
	s_add_i32 s7, s88, -2
	s_add_u32 s89, s60, 0x100
	v_mov_b32_e32 v1, v0
	v_ashrrev_i32_e32 v165, 31, v164
	s_addc_u32 s90, s61, 0
	v_lshl_add_u64 v[168:169], s[58:59], 0, v[152:153]
	v_lshl_add_u64 v[170:171], s[58:59], 0, v[154:155]
	s_mov_b32 s64, 0
	s_mov_b64 s[60:61], 0
	s_xor_b64 s[62:63], s[62:63], -1
	v_add_u32_e32 v1, s79, v173
	s_add_i32 s2, s64, 2
	ds_read_b128 v[132:135], v1
	ds_read_b128 v[136:139], v1 offset:1024
	ds_read_b128 v[140:143], v1 offset:2048
	ds_read_b128 v[178:181], v1 offset:3072
	v_add_u32_e32 v1, s80, v173
	s_add_u32 s65, s58, s60
	ds_read_b128 v[182:185], v1
	ds_read_b128 v[188:191], v1 offset:1024
	ds_read_b128 v[192:195], v1 offset:2048
	ds_read_b128 v[196:199], v1 offset:3072
	s_addc_u32 s66, s59, s61
	s_add_u32 s65, s65, 0x100
	s_addc_u32 s66, s66, 0
	s_add_u32 s75, s89, s60
	s_addc_u32 s91, s90, s61
	s_cmp_eq_u32 s7, s64
	s_cselect_b32 s67, s51, s66
	s_cselect_b32 s66, s50, s65
	s_cselect_b32 s65, s53, s91
	s_cselect_b32 s64, s52, s75
	v_lshl_add_u64 v[2:3], v[168:169], 0, s[60:61]
	s_add_i32 m0, s69, 0xc000
	ds_read_b128 v[200:203], v174
	ds_read_b128 v[204:207], v174 offset:1024
	ds_read_b128 v[208:211], v174 offset:2048
	ds_read_b128 v[212:215], v174 offset:3072
	ds_read_b128 v[216:219], v174 offset:4096
	ds_read_b128 v[220:223], v174 offset:5120
	ds_read_b128 v[224:227], v174 offset:6144
	ds_read_b128 v[228:231], v174 offset:7168
	global_load_lds_dwordx4 v[2:3], off
	v_lshl_add_u64 v[2:3], v[170:171], 0, s[60:61]
	s_add_i32 m0, s69, 0xe000
	s_nop 0
	global_load_lds_dwordx4 v[2:3], off
	s_waitcnt vmcnt(8) lgkmcnt(0)
	s_setprio 1
	s_barrier
	v_mfma_f32_16x16x32_bf16 v[128:131], v[132:135], v[200:203], 0
	v_mfma_f32_16x16x32_bf16 v[124:127], v[140:143], v[200:203], 0
	v_mfma_f32_16x16x32_bf16 v[112:115], v[132:135], v[208:211], 0
	v_mfma_f32_16x16x32_bf16 v[108:111], v[140:143], v[208:211], 0
	v_mfma_f32_16x16x32_bf16 v[96:99], v[132:135], v[216:219], 0
	v_mfma_f32_16x16x32_bf16 v[92:95], v[140:143], v[216:219], 0
	v_mfma_f32_16x16x32_bf16 v[80:83], v[132:135], v[224:227], 0
	v_mfma_f32_16x16x32_bf16 v[76:79], v[140:143], v[224:227], 0
	v_mfma_f32_16x16x32_bf16 v[128:131], v[136:139], v[204:207], v[128:131]
	v_mfma_f32_16x16x32_bf16 v[124:127], v[178:181], v[204:207], v[124:127]
	v_mfma_f32_16x16x32_bf16 v[112:115], v[136:139], v[212:215], v[112:115]
	v_mfma_f32_16x16x32_bf16 v[108:111], v[178:181], v[212:215], v[108:111]
	v_mfma_f32_16x16x32_bf16 v[96:99], v[136:139], v[220:223], v[96:99]
	v_mfma_f32_16x16x32_bf16 v[92:95], v[178:181], v[220:223], v[92:95]
	v_mfma_f32_16x16x32_bf16 v[80:83], v[136:139], v[228:231], v[80:83]
	v_mfma_f32_16x16x32_bf16 v[76:79], v[178:181], v[228:231], v[76:79]
	s_setprio 0
	s_setprio 1
	v_mfma_f32_16x16x32_bf16 v[120:123], v[182:185], v[200:203], 0
	v_mfma_f32_16x16x32_bf16 v[116:119], v[192:195], v[200:203], 0
	v_mfma_f32_16x16x32_bf16 v[104:107], v[182:185], v[208:211], 0
	v_mfma_f32_16x16x32_bf16 v[100:103], v[192:195], v[208:211], 0
	v_mfma_f32_16x16x32_bf16 v[88:91], v[182:185], v[216:219], 0
	v_mfma_f32_16x16x32_bf16 v[84:87], v[192:195], v[216:219], 0
	v_mfma_f32_16x16x32_bf16 v[72:75], v[182:185], v[224:227], 0
	v_mfma_f32_16x16x32_bf16 v[68:71], v[192:195], v[224:227], 0
	v_mfma_f32_16x16x32_bf16 v[120:123], v[188:191], v[204:207], v[120:123]
	v_mfma_f32_16x16x32_bf16 v[116:119], v[196:199], v[204:207], v[116:119]
	v_mfma_f32_16x16x32_bf16 v[104:107], v[188:191], v[212:215], v[104:107]
	v_mfma_f32_16x16x32_bf16 v[100:103], v[196:199], v[212:215], v[100:103]
	v_mfma_f32_16x16x32_bf16 v[88:91], v[188:191], v[220:223], v[88:91]
	v_mfma_f32_16x16x32_bf16 v[84:87], v[196:199], v[220:223], v[84:87]
	v_mfma_f32_16x16x32_bf16 v[72:75], v[188:191], v[228:231], v[72:75]
	v_mfma_f32_16x16x32_bf16 v[68:71], v[196:199], v[228:231], v[68:71]
	s_barrier
	s_setprio 0
	s_add_i32 s75, s79, s68
	v_lshl_add_u64 v[232:233], s[64:65], 0, v[148:149]
	s_mov_b32 m0, s75
	ds_read_b128 v[200:203], v174 offset:16384
	ds_read_b128 v[204:207], v174 offset:17408
	ds_read_b128 v[208:211], v174 offset:18432
	ds_read_b128 v[212:215], v174 offset:19456
	ds_read_b128 v[216:219], v174 offset:20480
	ds_read_b128 v[220:223], v174 offset:21504
	ds_read_b128 v[224:227], v174 offset:22528
	ds_read_b128 v[228:231], v174 offset:23552
	global_load_lds_dwordx4 v[232:233], off
	s_add_i32 m0, s75, 0x2000
	s_add_u32 s92, s64, 0xa0000
	v_lshl_add_u64 v[234:235], s[64:65], 0, v[144:145]
	s_addc_u32 s93, s65, 0
	s_add_i32 s75, s80, s68
	global_load_lds_dwordx4 v[234:235], off
	v_lshl_add_u64 v[2:3], s[92:93], 0, v[148:149]
	s_mov_b32 m0, s75
	v_lshl_add_u64 v[236:237], s[66:67], 0, v[150:151]
	global_load_lds_dwordx4 v[2:3], off
	v_lshl_add_u64 v[2:3], s[92:93], 0, v[144:145]
	s_add_i32 m0, s75, 0x2000
	v_lshl_add_u64 v[238:239], s[66:67], 0, v[146:147]
	global_load_lds_dwordx4 v[2:3], off
	s_mov_b32 m0, s69
	s_nop 0
	global_load_lds_dwordx4 v[236:237], off
	s_mov_b32 m0, s70
	s_nop 0
	global_load_lds_dwordx4 v[238:239], off
	s_waitcnt vmcnt(8) lgkmcnt(0)
	s_setprio 1
	s_barrier
	v_mfma_f32_16x16x32_bf16 v[64:67], v[132:135], v[200:203], 0
	v_mfma_f32_16x16x32_bf16 v[60:63], v[140:143], v[200:203], 0
	v_mfma_f32_16x16x32_bf16 v[48:51], v[132:135], v[208:211], 0
	v_mfma_f32_16x16x32_bf16 v[44:47], v[140:143], v[208:211], 0
	v_mfma_f32_16x16x32_bf16 v[32:35], v[132:135], v[216:219], 0
	v_mfma_f32_16x16x32_bf16 v[28:31], v[140:143], v[216:219], 0
	v_mfma_f32_16x16x32_bf16 v[16:19], v[132:135], v[224:227], 0
	v_mfma_f32_16x16x32_bf16 v[12:15], v[140:143], v[224:227], 0
	v_mfma_f32_16x16x32_bf16 v[64:67], v[136:139], v[204:207], v[64:67]
	v_mfma_f32_16x16x32_bf16 v[60:63], v[178:181], v[204:207], v[60:63]
	v_mfma_f32_16x16x32_bf16 v[48:51], v[136:139], v[212:215], v[48:51]
	v_mfma_f32_16x16x32_bf16 v[44:47], v[178:181], v[212:215], v[44:47]
	v_mfma_f32_16x16x32_bf16 v[32:35], v[136:139], v[220:223], v[32:35]
	v_mfma_f32_16x16x32_bf16 v[28:31], v[178:181], v[220:223], v[28:31]
	v_mfma_f32_16x16x32_bf16 v[16:19], v[136:139], v[228:231], v[16:19]
	v_mfma_f32_16x16x32_bf16 v[12:15], v[178:181], v[228:231], v[12:15]
	s_setprio 0
	s_setprio 1
	v_mfma_f32_16x16x32_bf16 v[56:59], v[182:185], v[200:203], 0
	v_mfma_f32_16x16x32_bf16 v[52:55], v[192:195], v[200:203], 0
	v_mfma_f32_16x16x32_bf16 v[40:43], v[182:185], v[208:211], 0
	v_mfma_f32_16x16x32_bf16 v[36:39], v[192:195], v[208:211], 0
	v_mfma_f32_16x16x32_bf16 v[24:27], v[182:185], v[216:219], 0
	v_mfma_f32_16x16x32_bf16 v[20:23], v[192:195], v[216:219], 0
	v_mfma_f32_16x16x32_bf16 v[8:11], v[182:185], v[224:227], 0
	v_mfma_f32_16x16x32_bf16 v[2:5], v[192:195], v[224:227], 0
	v_mfma_f32_16x16x32_bf16 v[56:59], v[188:191], v[204:207], v[56:59]
	v_mfma_f32_16x16x32_bf16 v[52:55], v[196:199], v[204:207], v[52:55]
	v_mfma_f32_16x16x32_bf16 v[40:43], v[188:191], v[212:215], v[40:43]
	v_mfma_f32_16x16x32_bf16 v[36:39], v[196:199], v[212:215], v[36:39]
	v_mfma_f32_16x16x32_bf16 v[24:27], v[188:191], v[220:223], v[24:27]
	v_mfma_f32_16x16x32_bf16 v[20:23], v[196:199], v[220:223], v[20:23]
	v_mfma_f32_16x16x32_bf16 v[8:11], v[188:191], v[228:231], v[8:11]
	v_mfma_f32_16x16x32_bf16 v[2:5], v[196:199], v[228:231], v[2:5]
	s_barrier
	s_setprio 0
	s_branch .Lpeel_mid_p3

.LBB0_599:
	v_add_u32_e32 v1, s79, v173
	s_add_i32 s2, s64, 2
	ds_read_b128 v[132:135], v1
	ds_read_b128 v[136:139], v1 offset:1024
	ds_read_b128 v[140:143], v1 offset:2048
	ds_read_b128 v[178:181], v1 offset:3072
	v_add_u32_e32 v1, s80, v173
	s_add_u32 s65, s58, s60
	ds_read_b128 v[182:185], v1
	ds_read_b128 v[188:191], v1 offset:1024
	ds_read_b128 v[192:195], v1 offset:2048
	ds_read_b128 v[196:199], v1 offset:3072
	s_addc_u32 s66, s59, s61
	s_add_u32 s65, s65, 0x100
	s_addc_u32 s66, s66, 0
	s_add_u32 s75, s89, s60
	s_addc_u32 s91, s90, s61
	s_cmp_eq_u32 s7, s64
	s_cselect_b32 s67, s51, s66
	s_cselect_b32 s66, s50, s65
	s_cselect_b32 s65, s53, s91
	s_cselect_b32 s64, s52, s75
	v_lshl_add_u64 v[2:3], v[168:169], 0, s[60:61]
	s_add_i32 m0, s69, 0xc000
	ds_read_b128 v[200:203], v174
	ds_read_b128 v[204:207], v174 offset:1024
	ds_read_b128 v[208:211], v174 offset:2048
	ds_read_b128 v[212:215], v174 offset:3072
	ds_read_b128 v[216:219], v174 offset:4096
	ds_read_b128 v[220:223], v174 offset:5120
	ds_read_b128 v[224:227], v174 offset:6144
	ds_read_b128 v[228:231], v174 offset:7168
	global_load_lds_dwordx4 v[2:3], off
	v_lshl_add_u64 v[2:3], v[170:171], 0, s[60:61]
	s_add_i32 m0, s69, 0xe000
	s_nop 0
	global_load_lds_dwordx4 v[2:3], off
	s_waitcnt vmcnt(8) lgkmcnt(0)
	s_setprio 1
	s_barrier
	v_mfma_f32_16x16x32_bf16 v[128:131], v[132:135], v[200:203], v[128:131]
	v_mfma_f32_16x16x32_bf16 v[124:127], v[140:143], v[200:203], v[124:127]
	v_mfma_f32_16x16x32_bf16 v[112:115], v[132:135], v[208:211], v[112:115]
	v_mfma_f32_16x16x32_bf16 v[108:111], v[140:143], v[208:211], v[108:111]
	v_mfma_f32_16x16x32_bf16 v[96:99], v[132:135], v[216:219], v[96:99]
	v_mfma_f32_16x16x32_bf16 v[92:95], v[140:143], v[216:219], v[92:95]
	v_mfma_f32_16x16x32_bf16 v[80:83], v[132:135], v[224:227], v[80:83]
	v_mfma_f32_16x16x32_bf16 v[76:79], v[140:143], v[224:227], v[76:79]
	v_mfma_f32_16x16x32_bf16 v[128:131], v[136:139], v[204:207], v[128:131]
	v_mfma_f32_16x16x32_bf16 v[124:127], v[178:181], v[204:207], v[124:127]
	v_mfma_f32_16x16x32_bf16 v[112:115], v[136:139], v[212:215], v[112:115]
	v_mfma_f32_16x16x32_bf16 v[108:111], v[178:181], v[212:215], v[108:111]
	v_mfma_f32_16x16x32_bf16 v[96:99], v[136:139], v[220:223], v[96:99]
	v_mfma_f32_16x16x32_bf16 v[92:95], v[178:181], v[220:223], v[92:95]
	v_mfma_f32_16x16x32_bf16 v[80:83], v[136:139], v[228:231], v[80:83]
	v_mfma_f32_16x16x32_bf16 v[76:79], v[178:181], v[228:231], v[76:79]
	s_setprio 0
	s_setprio 1
	v_mfma_f32_16x16x32_bf16 v[120:123], v[182:185], v[200:203], v[120:123]
	v_mfma_f32_16x16x32_bf16 v[116:119], v[192:195], v[200:203], v[116:119]
	v_mfma_f32_16x16x32_bf16 v[104:107], v[182:185], v[208:211], v[104:107]
	v_mfma_f32_16x16x32_bf16 v[100:103], v[192:195], v[208:211], v[100:103]
	v_mfma_f32_16x16x32_bf16 v[88:91], v[182:185], v[216:219], v[88:91]
	v_mfma_f32_16x16x32_bf16 v[84:87], v[192:195], v[216:219], v[84:87]
	v_mfma_f32_16x16x32_bf16 v[72:75], v[182:185], v[224:227], v[72:75]
	v_mfma_f32_16x16x32_bf16 v[68:71], v[192:195], v[224:227], v[68:71]
	v_mfma_f32_16x16x32_bf16 v[120:123], v[188:191], v[204:207], v[120:123]
	v_mfma_f32_16x16x32_bf16 v[116:119], v[196:199], v[204:207], v[116:119]
	v_mfma_f32_16x16x32_bf16 v[104:107], v[188:191], v[212:215], v[104:107]
	v_mfma_f32_16x16x32_bf16 v[100:103], v[196:199], v[212:215], v[100:103]
	v_mfma_f32_16x16x32_bf16 v[88:91], v[188:191], v[220:223], v[88:91]
	v_mfma_f32_16x16x32_bf16 v[84:87], v[196:199], v[220:223], v[84:87]
	v_mfma_f32_16x16x32_bf16 v[72:75], v[188:191], v[228:231], v[72:75]
	v_mfma_f32_16x16x32_bf16 v[68:71], v[196:199], v[228:231], v[68:71]
	s_barrier
	s_setprio 0
	s_add_i32 s75, s79, s68
	v_lshl_add_u64 v[232:233], s[64:65], 0, v[148:149]
	s_mov_b32 m0, s75
	ds_read_b128 v[200:203], v174 offset:16384
	ds_read_b128 v[204:207], v174 offset:17408
	ds_read_b128 v[208:211], v174 offset:18432
	ds_read_b128 v[212:215], v174 offset:19456
	ds_read_b128 v[216:219], v174 offset:20480
	ds_read_b128 v[220:223], v174 offset:21504
	ds_read_b128 v[224:227], v174 offset:22528
	ds_read_b128 v[228:231], v174 offset:23552
	global_load_lds_dwordx4 v[232:233], off
	s_add_i32 m0, s75, 0x2000
	s_add_u32 s92, s64, 0xa0000
	v_lshl_add_u64 v[234:235], s[64:65], 0, v[144:145]
	s_addc_u32 s93, s65, 0
	s_add_i32 s75, s80, s68
	global_load_lds_dwordx4 v[234:235], off
	v_lshl_add_u64 v[2:3], s[92:93], 0, v[148:149]
	s_mov_b32 m0, s75
	v_lshl_add_u64 v[236:237], s[66:67], 0, v[150:151]
	global_load_lds_dwordx4 v[2:3], off
	v_lshl_add_u64 v[2:3], s[92:93], 0, v[144:145]
	s_add_i32 m0, s75, 0x2000
	v_lshl_add_u64 v[238:239], s[66:67], 0, v[146:147]
	global_load_lds_dwordx4 v[2:3], off
	s_mov_b32 m0, s69
	s_nop 0
	global_load_lds_dwordx4 v[236:237], off
	s_mov_b32 m0, s70
	s_nop 0
	global_load_lds_dwordx4 v[238:239], off
	s_waitcnt vmcnt(8) lgkmcnt(0)
	s_setprio 1
	s_barrier
	v_mfma_f32_16x16x32_bf16 v[64:67], v[132:135], v[200:203], v[64:67]
	v_mfma_f32_16x16x32_bf16 v[60:63], v[140:143], v[200:203], v[60:63]
	v_mfma_f32_16x16x32_bf16 v[48:51], v[132:135], v[208:211], v[48:51]
	v_mfma_f32_16x16x32_bf16 v[44:47], v[140:143], v[208:211], v[44:47]
	v_mfma_f32_16x16x32_bf16 v[32:35], v[132:135], v[216:219], v[32:35]
	v_mfma_f32_16x16x32_bf16 v[28:31], v[140:143], v[216:219], v[28:31]
	v_mfma_f32_16x16x32_bf16 v[16:19], v[132:135], v[224:227], v[16:19]
	v_mfma_f32_16x16x32_bf16 v[12:15], v[140:143], v[224:227], v[12:15]
	v_mfma_f32_16x16x32_bf16 v[64:67], v[136:139], v[204:207], v[64:67]
	v_mfma_f32_16x16x32_bf16 v[60:63], v[178:181], v[204:207], v[60:63]
	v_mfma_f32_16x16x32_bf16 v[48:51], v[136:139], v[212:215], v[48:51]
	v_mfma_f32_16x16x32_bf16 v[44:47], v[178:181], v[212:215], v[44:47]
	v_mfma_f32_16x16x32_bf16 v[32:35], v[136:139], v[220:223], v[32:35]
	v_mfma_f32_16x16x32_bf16 v[28:31], v[178:181], v[220:223], v[28:31]
	v_mfma_f32_16x16x32_bf16 v[16:19], v[136:139], v[228:231], v[16:19]
	v_mfma_f32_16x16x32_bf16 v[12:15], v[178:181], v[228:231], v[12:15]
	s_setprio 0
	s_setprio 1
	v_mfma_f32_16x16x32_bf16 v[56:59], v[182:185], v[200:203], v[56:59]
	v_mfma_f32_16x16x32_bf16 v[52:55], v[192:195], v[200:203], v[52:55]
	v_mfma_f32_16x16x32_bf16 v[40:43], v[182:185], v[208:211], v[40:43]
	v_mfma_f32_16x16x32_bf16 v[36:39], v[192:195], v[208:211], v[36:39]
	v_mfma_f32_16x16x32_bf16 v[24:27], v[182:185], v[216:219], v[24:27]
	v_mfma_f32_16x16x32_bf16 v[20:23], v[192:195], v[216:219], v[20:23]
	v_mfma_f32_16x16x32_bf16 v[8:11], v[182:185], v[224:227], v[8:11]
	v_mfma_f32_16x16x32_bf16 v[2:5], v[192:195], v[224:227], v[4:7]
	v_mfma_f32_16x16x32_bf16 v[56:59], v[188:191], v[204:207], v[56:59]
	v_mfma_f32_16x16x32_bf16 v[52:55], v[196:199], v[204:207], v[52:55]
	v_mfma_f32_16x16x32_bf16 v[40:43], v[188:191], v[212:215], v[40:43]
	v_mfma_f32_16x16x32_bf16 v[36:39], v[196:199], v[212:215], v[36:39]
	v_mfma_f32_16x16x32_bf16 v[24:27], v[188:191], v[220:223], v[24:27]
	v_mfma_f32_16x16x32_bf16 v[20:23], v[196:199], v[220:223], v[20:23]
	v_mfma_f32_16x16x32_bf16 v[8:11], v[188:191], v[228:231], v[8:11]
	v_mfma_f32_16x16x32_bf16 v[2:5], v[196:199], v[228:231], v[2:5]
	s_barrier
	s_setprio 0
.Lpeel_mid_p3:
	s_add_i32 s75, 0, 0x18000
	v_add_u32_e32 v1, s75, v173
	s_add_i32 s91, 0, 0x1c000
	ds_read_b128 v[132:135], v1
	ds_read_b128 v[136:139], v1 offset:1024
	ds_read_b128 v[140:143], v1 offset:2048
	ds_read_b128 v[178:181], v1 offset:3072
	v_add_u32_e32 v1, s91, v173
	ds_read_b128 v[182:185], v1
	ds_read_b128 v[188:191], v1 offset:1024
	ds_read_b128 v[192:195], v1 offset:2048
	ds_read_b128 v[196:199], v1 offset:3072
	s_add_u32 s66, s66, 0xa0000
	s_addc_u32 s67, s67, 0
	s_mov_b32 m0, s71
	v_lshl_add_u64 v[6:7], s[66:67], 0, v[150:151]
	ds_read_b128 v[200:203], v174 offset:32768
	ds_read_b128 v[204:207], v174 offset:33792
	ds_read_b128 v[208:211], v174 offset:34816
	ds_read_b128 v[212:215], v174 offset:35840
	ds_read_b128 v[216:219], v174 offset:36864
	ds_read_b128 v[220:223], v174 offset:37888
	ds_read_b128 v[224:227], v174 offset:38912
	ds_read_b128 v[228:231], v174 offset:39936
	global_load_lds_dwordx4 v[6:7], off
	v_lshl_add_u64 v[6:7], s[66:67], 0, v[146:147]
	s_mov_b32 m0, s72
	s_nop 0
	global_load_lds_dwordx4 v[6:7], off
	s_waitcnt vmcnt(8) lgkmcnt(0)
	s_setprio 1
	s_barrier
	v_mfma_f32_16x16x32_bf16 v[128:131], v[132:135], v[200:203], v[128:131]
	v_mfma_f32_16x16x32_bf16 v[124:127], v[140:143], v[200:203], v[124:127]
	v_mfma_f32_16x16x32_bf16 v[112:115], v[132:135], v[208:211], v[112:115]
	v_mfma_f32_16x16x32_bf16 v[108:111], v[140:143], v[208:211], v[108:111]
	v_mfma_f32_16x16x32_bf16 v[96:99], v[132:135], v[216:219], v[96:99]
	v_mfma_f32_16x16x32_bf16 v[92:95], v[140:143], v[216:219], v[92:95]
	v_mfma_f32_16x16x32_bf16 v[80:83], v[132:135], v[224:227], v[80:83]
	v_mfma_f32_16x16x32_bf16 v[76:79], v[140:143], v[224:227], v[76:79]
	v_mfma_f32_16x16x32_bf16 v[128:131], v[136:139], v[204:207], v[128:131]
	v_mfma_f32_16x16x32_bf16 v[124:127], v[178:181], v[204:207], v[124:127]
	v_mfma_f32_16x16x32_bf16 v[112:115], v[136:139], v[212:215], v[112:115]
	v_mfma_f32_16x16x32_bf16 v[108:111], v[178:181], v[212:215], v[108:111]
	v_mfma_f32_16x16x32_bf16 v[96:99], v[136:139], v[220:223], v[96:99]
	v_mfma_f32_16x16x32_bf16 v[92:95], v[178:181], v[220:223], v[92:95]
	v_mfma_f32_16x16x32_bf16 v[80:83], v[136:139], v[228:231], v[80:83]
	v_mfma_f32_16x16x32_bf16 v[76:79], v[178:181], v[228:231], v[76:79]
	s_setprio 0
	s_setprio 1
	v_mfma_f32_16x16x32_bf16 v[120:123], v[182:185], v[200:203], v[120:123]
	v_mfma_f32_16x16x32_bf16 v[116:119], v[192:195], v[200:203], v[116:119]
	v_mfma_f32_16x16x32_bf16 v[104:107], v[182:185], v[208:211], v[104:107]
	v_mfma_f32_16x16x32_bf16 v[100:103], v[192:195], v[208:211], v[100:103]
	v_mfma_f32_16x16x32_bf16 v[88:91], v[182:185], v[216:219], v[88:91]
	v_mfma_f32_16x16x32_bf16 v[84:87], v[192:195], v[216:219], v[84:87]
	v_mfma_f32_16x16x32_bf16 v[72:75], v[182:185], v[224:227], v[72:75]
	v_mfma_f32_16x16x32_bf16 v[68:71], v[192:195], v[224:227], v[68:71]
	v_mfma_f32_16x16x32_bf16 v[120:123], v[188:191], v[204:207], v[120:123]
	v_mfma_f32_16x16x32_bf16 v[116:119], v[196:199], v[204:207], v[116:119]
	v_mfma_f32_16x16x32_bf16 v[104:107], v[188:191], v[212:215], v[104:107]
	v_mfma_f32_16x16x32_bf16 v[100:103], v[196:199], v[212:215], v[100:103]
	v_mfma_f32_16x16x32_bf16 v[88:91], v[188:191], v[220:223], v[88:91]
	v_mfma_f32_16x16x32_bf16 v[84:87], v[196:199], v[220:223], v[84:87]
	v_mfma_f32_16x16x32_bf16 v[72:75], v[188:191], v[228:231], v[72:75]
	v_mfma_f32_16x16x32_bf16 v[68:71], v[196:199], v[228:231], v[68:71]
	s_barrier
	s_setprio 0
	s_add_i32 s66, s75, s68
	v_lshl_add_u64 v[6:7], v[232:233], 0, s[14:15]
	s_mov_b32 m0, s66
	ds_read_b128 v[200:203], v174 offset:49152
	ds_read_b128 v[204:207], v174 offset:50176
	ds_read_b128 v[208:211], v174 offset:51200
	ds_read_b128 v[212:215], v174 offset:52224
	ds_read_b128 v[216:219], v174 offset:53248
	ds_read_b128 v[220:223], v174 offset:54272
	ds_read_b128 v[224:227], v174 offset:55296
	ds_read_b128 v[228:231], v174 offset:56320
	global_load_lds_dwordx4 v[6:7], off
	s_add_i32 m0, s66, 0x2000
	s_add_u32 s64, s64, 0xa0080
	v_lshl_add_u64 v[6:7], v[234:235], 0, s[14:15]
	s_addc_u32 s65, s65, 0
	s_add_i32 s66, s91, s68
	global_load_lds_dwordx4 v[6:7], off
	v_lshl_add_u64 v[6:7], s[64:65], 0, v[148:149]
	s_mov_b32 m0, s66
	s_nop 0
	global_load_lds_dwordx4 v[6:7], off
	v_lshl_add_u64 v[6:7], s[64:65], 0, v[144:145]
	s_add_i32 m0, s66, 0x2000
	s_nop 0
	global_load_lds_dwordx4 v[6:7], off
	v_lshl_add_u64 v[6:7], v[236:237], 0, s[14:15]
	s_mov_b32 m0, s73
	s_nop 0
	global_load_lds_dwordx4 v[6:7], off
	v_lshl_add_u64 v[6:7], v[238:239], 0, s[14:15]
	s_mov_b32 m0, s76
	s_nop 0
	global_load_lds_dwordx4 v[6:7], off
	s_waitcnt vmcnt(8) lgkmcnt(0)
	s_setprio 1
	s_barrier
	v_mfma_f32_16x16x32_bf16 v[64:67], v[132:135], v[200:203], v[64:67]
	v_mfma_f32_16x16x32_bf16 v[60:63], v[140:143], v[200:203], v[60:63]
	v_mfma_f32_16x16x32_bf16 v[48:51], v[132:135], v[208:211], v[48:51]
	v_mfma_f32_16x16x32_bf16 v[44:47], v[140:143], v[208:211], v[44:47]
	v_mfma_f32_16x16x32_bf16 v[32:35], v[132:135], v[216:219], v[32:35]
	v_mfma_f32_16x16x32_bf16 v[28:31], v[140:143], v[216:219], v[28:31]
	v_mfma_f32_16x16x32_bf16 v[16:19], v[132:135], v[224:227], v[16:19]
	v_mfma_f32_16x16x32_bf16 v[12:15], v[140:143], v[224:227], v[12:15]
	v_mfma_f32_16x16x32_bf16 v[64:67], v[136:139], v[204:207], v[64:67]
	v_mfma_f32_16x16x32_bf16 v[60:63], v[178:181], v[204:207], v[60:63]
	v_mfma_f32_16x16x32_bf16 v[48:51], v[136:139], v[212:215], v[48:51]
	s_add_u32 s60, s60, 0x100
	v_mfma_f32_16x16x32_bf16 v[44:47], v[178:181], v[212:215], v[44:47]
	s_addc_u32 s61, s61, 0
	v_mfma_f32_16x16x32_bf16 v[32:35], v[136:139], v[220:223], v[32:35]
	s_cmp_eq_u32 s2, 16
	v_mfma_f32_16x16x32_bf16 v[28:31], v[178:181], v[220:223], v[28:31]
	s_cselect_b32 s100, 1, 0
	v_mfma_f32_16x16x32_bf16 v[16:19], v[136:139], v[228:231], v[16:19]
	s_cmp_eq_u32 s2, 24
	v_mfma_f32_16x16x32_bf16 v[12:15], v[178:181], v[228:231], v[12:15]
	s_cselect_b32 s101, 1, 0
	s_setprio 0
	s_setprio 1
	v_mfma_f32_16x16x32_bf16 v[56:59], v[182:185], v[200:203], v[56:59]
	s_or_b32 s100, s100, s101
	v_mfma_f32_16x16x32_bf16 v[52:55], v[192:195], v[200:203], v[52:55]
	s_cmp_eq_u64 s[62:63], 0
	v_mfma_f32_16x16x32_bf16 v[40:43], v[182:185], v[208:211], v[40:43]
	s_cselect_b32 s100, s100, 0
	v_mfma_f32_16x16x32_bf16 v[36:39], v[192:195], v[208:211], v[36:39]
	s_cmp_ge_i32 s2, s88
	v_mfma_f32_16x16x32_bf16 v[24:27], v[182:185], v[216:219], v[24:27]
	s_cselect_b32 s67, 1, 0
	v_mfma_f32_16x16x32_bf16 v[20:23], v[192:195], v[216:219], v[20:23]
	s_cmp_eq_u64 s[18:19], 0
	v_mfma_f32_16x16x32_bf16 v[6:9], v[182:185], v[224:227], v[8:11]
	s_cselect_b32 s66, 0, s100
	v_mfma_f32_16x16x32_bf16 v[2:5], v[192:195], v[224:227], v[2:5]
	s_cselect_b32 s100, s100, 0
	v_mfma_f32_16x16x32_bf16 v[56:59], v[188:191], v[204:207], v[56:59]
	s_or_b32 s66, s66, s67
	v_mfma_f32_16x16x32_bf16 v[52:55], v[196:199], v[204:207], v[52:55]
	s_mov_b32 s64, s2
	v_mfma_f32_16x16x32_bf16 v[40:43], v[188:191], v[212:215], v[40:43]
	s_cmp_lg_u32 s100, 0
	v_mfma_f32_16x16x32_bf16 v[36:39], v[196:199], v[212:215], v[36:39]
	v_mfma_f32_16x16x32_bf16 v[24:27], v[188:191], v[220:223], v[24:27]
	v_mfma_f32_16x16x32_bf16 v[20:23], v[196:199], v[220:223], v[20:23]
	v_mfma_f32_16x16x32_bf16 v[8:11], v[188:191], v[228:231], v[6:9]
	v_mfma_f32_16x16x32_bf16 v[4:7], v[196:199], v[228:231], v[2:5]
	s_setprio 0
	s_cbranch_scc0 .Lhk_skipB

.LBB0_671:
	s_add_u32 s6, s6, 0x80080
	s_addc_u32 s7, s7, 0
	s_add_u32 s5, s40, 0x100
	s_addc_u32 s25, s41, 0
	s_mov_b32 s56, -2
	ds_read_b128 v[128:131], v185
	ds_read_b128 v[132:135], v185 offset:1024
	ds_read_b128 v[136:139], v185 offset:2048
	ds_read_b128 v[140:143], v185 offset:3072
	ds_read_b128 v[162:165], v186
	ds_read_b128 v[166:169], v186 offset:1024
	ds_read_b128 v[170:173], v186 offset:2048
	ds_read_b128 v[174:177], v186 offset:3072
	s_add_u32 s38, s6, 0xfff80080
	s_addc_u32 s39, s7, -1
	s_cmp_eq_u32 s56, 28
	s_cselect_b32 s41, s27, s39
	s_cselect_b32 s40, s26, s38
	s_cselect_b32 s39, s23, s25
	s_cselect_b32 s38, s22, s5
	v_lshl_add_u64 v[182:183], s[6:7], 0, v[158:159]
	s_add_i32 m0, s42, 0xc000
	ds_read_b128 v[178:181], v188
	ds_read_b128 v[192:195], v188 offset:1024
	ds_read_b128 v[196:199], v188 offset:2048
	ds_read_b128 v[200:203], v188 offset:3072
	ds_read_b128 v[204:207], v188 offset:4096
	ds_read_b128 v[208:211], v188 offset:5120
	ds_read_b128 v[212:215], v188 offset:6144
	ds_read_b128 v[216:219], v188 offset:7168
	global_load_lds_dwordx4 v[182:183], off
	v_lshl_add_u64 v[182:183], s[6:7], 0, v[160:161]
	s_add_i32 m0, s42, 0xe000
	s_nop 0
	global_load_lds_dwordx4 v[182:183], off
	s_waitcnt vmcnt(8) lgkmcnt(0)
	s_setprio 1
	s_barrier
	v_mfma_f32_16x16x32_bf16 v[124:127], v[128:131], v[178:181], 0
	v_mfma_f32_16x16x32_bf16 v[120:123], v[136:139], v[178:181], 0
	v_mfma_f32_16x16x32_bf16 v[108:111], v[128:131], v[196:199], 0
	v_mfma_f32_16x16x32_bf16 v[104:107], v[136:139], v[196:199], 0
	v_mfma_f32_16x16x32_bf16 v[92:95], v[128:131], v[204:207], 0
	v_mfma_f32_16x16x32_bf16 v[88:91], v[136:139], v[204:207], 0
	v_mfma_f32_16x16x32_bf16 v[76:79], v[128:131], v[212:215], 0
	v_mfma_f32_16x16x32_bf16 v[72:75], v[136:139], v[212:215], 0
	v_mfma_f32_16x16x32_bf16 v[124:127], v[132:135], v[192:195], v[124:127]
	v_mfma_f32_16x16x32_bf16 v[120:123], v[140:143], v[192:195], v[120:123]
	v_mfma_f32_16x16x32_bf16 v[108:111], v[132:135], v[200:203], v[108:111]
	v_mfma_f32_16x16x32_bf16 v[104:107], v[140:143], v[200:203], v[104:107]
	v_mfma_f32_16x16x32_bf16 v[92:95], v[132:135], v[208:211], v[92:95]
	v_mfma_f32_16x16x32_bf16 v[88:91], v[140:143], v[208:211], v[88:91]
	v_mfma_f32_16x16x32_bf16 v[76:79], v[132:135], v[216:219], v[76:79]
	v_mfma_f32_16x16x32_bf16 v[72:75], v[140:143], v[216:219], v[72:75]
	s_setprio 0
	s_setprio 1
	v_mfma_f32_16x16x32_bf16 v[116:119], v[162:165], v[178:181], 0
	v_mfma_f32_16x16x32_bf16 v[112:115], v[170:173], v[178:181], 0
	v_mfma_f32_16x16x32_bf16 v[100:103], v[162:165], v[196:199], 0
	v_mfma_f32_16x16x32_bf16 v[96:99], v[170:173], v[196:199], 0
	v_mfma_f32_16x16x32_bf16 v[84:87], v[162:165], v[204:207], 0
	v_mfma_f32_16x16x32_bf16 v[80:83], v[170:173], v[204:207], 0
	v_mfma_f32_16x16x32_bf16 v[68:71], v[162:165], v[212:215], 0
	v_mfma_f32_16x16x32_bf16 v[64:67], v[170:173], v[212:215], 0
	v_mfma_f32_16x16x32_bf16 v[116:119], v[166:169], v[192:195], v[116:119]
	v_mfma_f32_16x16x32_bf16 v[112:115], v[174:177], v[192:195], v[112:115]
	v_mfma_f32_16x16x32_bf16 v[100:103], v[166:169], v[200:203], v[100:103]
	v_mfma_f32_16x16x32_bf16 v[96:99], v[174:177], v[200:203], v[96:99]
	v_mfma_f32_16x16x32_bf16 v[84:87], v[166:169], v[208:211], v[84:87]
	v_mfma_f32_16x16x32_bf16 v[80:83], v[174:177], v[208:211], v[80:83]
	v_mfma_f32_16x16x32_bf16 v[68:71], v[166:169], v[216:219], v[68:71]
	v_mfma_f32_16x16x32_bf16 v[64:67], v[174:177], v[216:219], v[64:67]
	s_barrier
	s_setprio 0
	s_add_i32 s57, s51, s35
	v_lshl_add_u64 v[182:183], s[38:39], 0, v[148:149]
	s_mov_b32 m0, s57
	ds_read_b128 v[178:181], v188 offset:16384
	ds_read_b128 v[192:195], v188 offset:17408
	ds_read_b128 v[196:199], v188 offset:18432
	ds_read_b128 v[200:203], v188 offset:19456
	ds_read_b128 v[204:207], v188 offset:20480
	ds_read_b128 v[208:211], v188 offset:21504
	ds_read_b128 v[212:215], v188 offset:22528
	ds_read_b128 v[216:219], v188 offset:23552
	global_load_lds_dwordx4 v[182:183], off
	s_add_i32 m0, s57, 0x2000
	s_add_u32 s58, s38, 0x80000
	v_lshl_add_u64 v[220:221], s[38:39], 0, v[144:145]
	s_addc_u32 s59, s39, 0
	s_add_i32 s57, s52, s35
	global_load_lds_dwordx4 v[220:221], off
	v_lshl_add_u64 v[222:223], s[58:59], 0, v[148:149]
	s_mov_b32 m0, s57
	v_lshl_add_u64 v[224:225], s[40:41], 0, v[146:147]
	global_load_lds_dwordx4 v[222:223], off
	v_lshl_add_u64 v[222:223], s[58:59], 0, v[144:145]
	s_add_i32 m0, s57, 0x2000
	s_nop 0
	global_load_lds_dwordx4 v[222:223], off
	v_lshl_add_u64 v[222:223], s[40:41], 0, v[150:151]
	s_mov_b32 m0, s42
	s_nop 0
	global_load_lds_dwordx4 v[222:223], off
	s_mov_b32 m0, s43
	s_nop 0
	global_load_lds_dwordx4 v[224:225], off
	s_waitcnt vmcnt(8) lgkmcnt(0)
	s_setprio 1
	s_barrier
	v_mfma_f32_16x16x32_bf16 v[60:63], v[128:131], v[178:181], 0
	v_mfma_f32_16x16x32_bf16 v[56:59], v[136:139], v[178:181], 0
	v_mfma_f32_16x16x32_bf16 v[44:47], v[128:131], v[196:199], 0
	v_mfma_f32_16x16x32_bf16 v[40:43], v[136:139], v[196:199], 0
	v_mfma_f32_16x16x32_bf16 v[28:31], v[128:131], v[204:207], 0
	v_mfma_f32_16x16x32_bf16 v[24:27], v[136:139], v[204:207], 0
	v_mfma_f32_16x16x32_bf16 v[12:15], v[128:131], v[212:215], 0
	v_mfma_f32_16x16x32_bf16 v[8:11], v[136:139], v[212:215], 0
	v_mfma_f32_16x16x32_bf16 v[60:63], v[132:135], v[192:195], v[60:63]
	v_mfma_f32_16x16x32_bf16 v[56:59], v[140:143], v[192:195], v[56:59]
	v_mfma_f32_16x16x32_bf16 v[44:47], v[132:135], v[200:203], v[44:47]
	v_mfma_f32_16x16x32_bf16 v[40:43], v[140:143], v[200:203], v[40:43]
	v_mfma_f32_16x16x32_bf16 v[28:31], v[132:135], v[208:211], v[28:31]
	v_mfma_f32_16x16x32_bf16 v[24:27], v[140:143], v[208:211], v[24:27]
	v_mfma_f32_16x16x32_bf16 v[12:15], v[132:135], v[216:219], v[12:15]
	v_mfma_f32_16x16x32_bf16 v[8:11], v[140:143], v[216:219], v[8:11]
	s_setprio 0
	s_setprio 1
	v_mfma_f32_16x16x32_bf16 v[52:55], v[162:165], v[178:181], 0
	v_mfma_f32_16x16x32_bf16 v[48:51], v[170:173], v[178:181], 0
	v_mfma_f32_16x16x32_bf16 v[36:39], v[162:165], v[196:199], 0
	v_mfma_f32_16x16x32_bf16 v[32:35], v[170:173], v[196:199], 0
	v_mfma_f32_16x16x32_bf16 v[20:23], v[162:165], v[204:207], 0
	v_mfma_f32_16x16x32_bf16 v[16:19], v[170:173], v[204:207], 0
	v_mfma_f32_16x16x32_bf16 v[4:7], v[162:165], v[212:215], 0
	v_mfma_f32_16x16x32_bf16 v[0:3], v[170:173], v[212:215], 0
	v_mfma_f32_16x16x32_bf16 v[52:55], v[166:169], v[192:195], v[52:55]
	v_mfma_f32_16x16x32_bf16 v[48:51], v[174:177], v[192:195], v[48:51]
	v_mfma_f32_16x16x32_bf16 v[36:39], v[166:169], v[200:203], v[36:39]
	v_mfma_f32_16x16x32_bf16 v[32:35], v[174:177], v[200:203], v[32:35]
	v_mfma_f32_16x16x32_bf16 v[20:23], v[166:169], v[208:211], v[20:23]
	v_mfma_f32_16x16x32_bf16 v[16:19], v[174:177], v[208:211], v[16:19]
	v_mfma_f32_16x16x32_bf16 v[4:7], v[166:169], v[216:219], v[4:7]
	v_mfma_f32_16x16x32_bf16 v[0:3], v[174:177], v[216:219], v[0:3]
	s_barrier
	s_setprio 0
	s_branch .Lpeel_mid_p4
	s_nop 0
	s_nop 0
.LBB0_672:
	ds_read_b128 v[128:131], v185
	ds_read_b128 v[132:135], v185 offset:1024
	ds_read_b128 v[136:139], v185 offset:2048
	ds_read_b128 v[140:143], v185 offset:3072
	ds_read_b128 v[162:165], v186
	ds_read_b128 v[166:169], v186 offset:1024
	ds_read_b128 v[170:173], v186 offset:2048
	ds_read_b128 v[174:177], v186 offset:3072
	s_add_u32 s38, s6, 0xfff80080
	s_addc_u32 s39, s7, -1
	s_cmp_eq_u32 s56, 28
	s_cselect_b32 s41, s27, s39
	s_cselect_b32 s40, s26, s38
	s_cselect_b32 s39, s23, s25
	s_cselect_b32 s38, s22, s5
	v_lshl_add_u64 v[182:183], s[6:7], 0, v[158:159]
	s_add_i32 m0, s42, 0xc000
	ds_read_b128 v[178:181], v188
	ds_read_b128 v[192:195], v188 offset:1024
	ds_read_b128 v[196:199], v188 offset:2048
	ds_read_b128 v[200:203], v188 offset:3072
	ds_read_b128 v[204:207], v188 offset:4096
	ds_read_b128 v[208:211], v188 offset:5120
	ds_read_b128 v[212:215], v188 offset:6144
	ds_read_b128 v[216:219], v188 offset:7168
	global_load_lds_dwordx4 v[182:183], off
	v_lshl_add_u64 v[182:183], s[6:7], 0, v[160:161]
	s_add_i32 m0, s42, 0xe000
	s_nop 0
	global_load_lds_dwordx4 v[182:183], off
	s_waitcnt vmcnt(8) lgkmcnt(0)
	s_setprio 1
	s_barrier
	v_mfma_f32_16x16x32_bf16 v[124:127], v[128:131], v[178:181], v[124:127]
	v_mfma_f32_16x16x32_bf16 v[120:123], v[136:139], v[178:181], v[120:123]
	v_mfma_f32_16x16x32_bf16 v[108:111], v[128:131], v[196:199], v[108:111]
	v_mfma_f32_16x16x32_bf16 v[104:107], v[136:139], v[196:199], v[104:107]
	v_mfma_f32_16x16x32_bf16 v[92:95], v[128:131], v[204:207], v[92:95]
	v_mfma_f32_16x16x32_bf16 v[88:91], v[136:139], v[204:207], v[88:91]
	v_mfma_f32_16x16x32_bf16 v[76:79], v[128:131], v[212:215], v[76:79]
	v_mfma_f32_16x16x32_bf16 v[72:75], v[136:139], v[212:215], v[72:75]
	v_mfma_f32_16x16x32_bf16 v[124:127], v[132:135], v[192:195], v[124:127]
	v_mfma_f32_16x16x32_bf16 v[120:123], v[140:143], v[192:195], v[120:123]
	v_mfma_f32_16x16x32_bf16 v[108:111], v[132:135], v[200:203], v[108:111]
	v_mfma_f32_16x16x32_bf16 v[104:107], v[140:143], v[200:203], v[104:107]
	v_mfma_f32_16x16x32_bf16 v[92:95], v[132:135], v[208:211], v[92:95]
	v_mfma_f32_16x16x32_bf16 v[88:91], v[140:143], v[208:211], v[88:91]
	v_mfma_f32_16x16x32_bf16 v[76:79], v[132:135], v[216:219], v[76:79]
	v_mfma_f32_16x16x32_bf16 v[72:75], v[140:143], v[216:219], v[72:75]
	s_setprio 0
	s_setprio 1
	v_mfma_f32_16x16x32_bf16 v[116:119], v[162:165], v[178:181], v[116:119]
	v_mfma_f32_16x16x32_bf16 v[112:115], v[170:173], v[178:181], v[112:115]
	v_mfma_f32_16x16x32_bf16 v[100:103], v[162:165], v[196:199], v[100:103]
	v_mfma_f32_16x16x32_bf16 v[96:99], v[170:173], v[196:199], v[96:99]
	v_mfma_f32_16x16x32_bf16 v[84:87], v[162:165], v[204:207], v[84:87]
	v_mfma_f32_16x16x32_bf16 v[80:83], v[170:173], v[204:207], v[80:83]
	v_mfma_f32_16x16x32_bf16 v[68:71], v[162:165], v[212:215], v[68:71]
	v_mfma_f32_16x16x32_bf16 v[64:67], v[170:173], v[212:215], v[64:67]
	v_mfma_f32_16x16x32_bf16 v[116:119], v[166:169], v[192:195], v[116:119]
	v_mfma_f32_16x16x32_bf16 v[112:115], v[174:177], v[192:195], v[112:115]
	v_mfma_f32_16x16x32_bf16 v[100:103], v[166:169], v[200:203], v[100:103]
	v_mfma_f32_16x16x32_bf16 v[96:99], v[174:177], v[200:203], v[96:99]
	v_mfma_f32_16x16x32_bf16 v[84:87], v[166:169], v[208:211], v[84:87]
	v_mfma_f32_16x16x32_bf16 v[80:83], v[174:177], v[208:211], v[80:83]
	v_mfma_f32_16x16x32_bf16 v[68:71], v[166:169], v[216:219], v[68:71]
	v_mfma_f32_16x16x32_bf16 v[64:67], v[174:177], v[216:219], v[64:67]
	s_barrier
	s_setprio 0
	s_add_i32 s57, s51, s35
	v_lshl_add_u64 v[182:183], s[38:39], 0, v[148:149]
	s_mov_b32 m0, s57
	ds_read_b128 v[178:181], v188 offset:16384
	ds_read_b128 v[192:195], v188 offset:17408
	ds_read_b128 v[196:199], v188 offset:18432
	ds_read_b128 v[200:203], v188 offset:19456
	ds_read_b128 v[204:207], v188 offset:20480
	ds_read_b128 v[208:211], v188 offset:21504
	ds_read_b128 v[212:215], v188 offset:22528
	ds_read_b128 v[216:219], v188 offset:23552
	global_load_lds_dwordx4 v[182:183], off
	s_add_i32 m0, s57, 0x2000
	s_add_u32 s58, s38, 0x80000
	v_lshl_add_u64 v[220:221], s[38:39], 0, v[144:145]
	s_addc_u32 s59, s39, 0
	s_add_i32 s57, s52, s35
	global_load_lds_dwordx4 v[220:221], off
	v_lshl_add_u64 v[222:223], s[58:59], 0, v[148:149]
	s_mov_b32 m0, s57
	v_lshl_add_u64 v[224:225], s[40:41], 0, v[146:147]
	global_load_lds_dwordx4 v[222:223], off
	v_lshl_add_u64 v[222:223], s[58:59], 0, v[144:145]
	s_add_i32 m0, s57, 0x2000
	s_nop 0
	global_load_lds_dwordx4 v[222:223], off
	v_lshl_add_u64 v[222:223], s[40:41], 0, v[150:151]
	s_mov_b32 m0, s42
	s_nop 0
	global_load_lds_dwordx4 v[222:223], off
	s_mov_b32 m0, s43
	s_nop 0
	global_load_lds_dwordx4 v[224:225], off
	s_waitcnt vmcnt(8) lgkmcnt(0)
	s_setprio 1
	s_barrier
	v_mfma_f32_16x16x32_bf16 v[60:63], v[128:131], v[178:181], v[60:63]
	v_mfma_f32_16x16x32_bf16 v[56:59], v[136:139], v[178:181], v[56:59]
	v_mfma_f32_16x16x32_bf16 v[44:47], v[128:131], v[196:199], v[44:47]
	v_mfma_f32_16x16x32_bf16 v[40:43], v[136:139], v[196:199], v[40:43]
	v_mfma_f32_16x16x32_bf16 v[28:31], v[128:131], v[204:207], v[28:31]
	v_mfma_f32_16x16x32_bf16 v[24:27], v[136:139], v[204:207], v[24:27]
	v_mfma_f32_16x16x32_bf16 v[12:15], v[128:131], v[212:215], v[12:15]
	v_mfma_f32_16x16x32_bf16 v[8:11], v[136:139], v[212:215], v[8:11]
	v_mfma_f32_16x16x32_bf16 v[60:63], v[132:135], v[192:195], v[60:63]
	v_mfma_f32_16x16x32_bf16 v[56:59], v[140:143], v[192:195], v[56:59]
	v_mfma_f32_16x16x32_bf16 v[44:47], v[132:135], v[200:203], v[44:47]
	v_mfma_f32_16x16x32_bf16 v[40:43], v[140:143], v[200:203], v[40:43]
	v_mfma_f32_16x16x32_bf16 v[28:31], v[132:135], v[208:211], v[28:31]
	v_mfma_f32_16x16x32_bf16 v[24:27], v[140:143], v[208:211], v[24:27]
	v_mfma_f32_16x16x32_bf16 v[12:15], v[132:135], v[216:219], v[12:15]
	v_mfma_f32_16x16x32_bf16 v[8:11], v[140:143], v[216:219], v[8:11]
	s_setprio 0
	s_setprio 1
	v_mfma_f32_16x16x32_bf16 v[52:55], v[162:165], v[178:181], v[52:55]
	v_mfma_f32_16x16x32_bf16 v[48:51], v[170:173], v[178:181], v[48:51]
	v_mfma_f32_16x16x32_bf16 v[36:39], v[162:165], v[196:199], v[36:39]
	v_mfma_f32_16x16x32_bf16 v[32:35], v[170:173], v[196:199], v[32:35]
	v_mfma_f32_16x16x32_bf16 v[20:23], v[162:165], v[204:207], v[20:23]
	v_mfma_f32_16x16x32_bf16 v[16:19], v[170:173], v[204:207], v[16:19]
	v_mfma_f32_16x16x32_bf16 v[4:7], v[162:165], v[212:215], v[4:7]
	v_mfma_f32_16x16x32_bf16 v[0:3], v[170:173], v[212:215], v[0:3]
	v_mfma_f32_16x16x32_bf16 v[52:55], v[166:169], v[192:195], v[52:55]
	v_mfma_f32_16x16x32_bf16 v[48:51], v[174:177], v[192:195], v[48:51]
	v_mfma_f32_16x16x32_bf16 v[36:39], v[166:169], v[200:203], v[36:39]
	v_mfma_f32_16x16x32_bf16 v[32:35], v[174:177], v[200:203], v[32:35]
	v_mfma_f32_16x16x32_bf16 v[20:23], v[166:169], v[208:211], v[20:23]
	v_mfma_f32_16x16x32_bf16 v[16:19], v[174:177], v[208:211], v[16:19]
	v_mfma_f32_16x16x32_bf16 v[4:7], v[166:169], v[216:219], v[4:7]
	v_mfma_f32_16x16x32_bf16 v[0:3], v[174:177], v[216:219], v[0:3]
	s_barrier
	s_setprio 0
.Lpeel_mid_p4:
	s_add_i32 s57, 0, 0x18000
	s_add_i32 s58, 0, 0x1c000
	v_add_u32_e32 v140, s57, v184
	v_add_u32_e32 v174, s58, v184
	ds_read_b128 v[128:131], v140
	ds_read_b128 v[132:135], v140 offset:1024
	ds_read_b128 v[136:139], v140 offset:2048
	ds_read_b128 v[140:143], v140 offset:3072
	ds_read_b128 v[162:165], v174
	ds_read_b128 v[166:169], v174 offset:1024
	ds_read_b128 v[170:173], v174 offset:2048
	ds_read_b128 v[174:177], v174 offset:3072
	s_add_u32 s40, s40, 0x80000
	s_addc_u32 s41, s41, 0
	s_mov_b32 m0, s44
	v_lshl_add_u64 v[226:227], s[40:41], 0, v[150:151]
	ds_read_b128 v[178:181], v188 offset:32768
	ds_read_b128 v[192:195], v188 offset:33792
	ds_read_b128 v[196:199], v188 offset:34816
	ds_read_b128 v[200:203], v188 offset:35840
	ds_read_b128 v[204:207], v188 offset:36864
	ds_read_b128 v[208:211], v188 offset:37888
	ds_read_b128 v[212:215], v188 offset:38912
	ds_read_b128 v[216:219], v188 offset:39936
	global_load_lds_dwordx4 v[226:227], off
	v_lshl_add_u64 v[226:227], s[40:41], 0, v[146:147]
	s_mov_b32 m0, s45
	s_nop 0
	global_load_lds_dwordx4 v[226:227], off
	s_waitcnt vmcnt(8) lgkmcnt(0)
	s_setprio 1
	s_barrier
	v_mfma_f32_16x16x32_bf16 v[124:127], v[128:131], v[178:181], v[124:127]
	v_mfma_f32_16x16x32_bf16 v[120:123], v[136:139], v[178:181], v[120:123]
	v_mfma_f32_16x16x32_bf16 v[108:111], v[128:131], v[196:199], v[108:111]
	v_mfma_f32_16x16x32_bf16 v[104:107], v[136:139], v[196:199], v[104:107]
	v_mfma_f32_16x16x32_bf16 v[92:95], v[128:131], v[204:207], v[92:95]
	v_mfma_f32_16x16x32_bf16 v[88:91], v[136:139], v[204:207], v[88:91]
	v_mfma_f32_16x16x32_bf16 v[76:79], v[128:131], v[212:215], v[76:79]
	v_mfma_f32_16x16x32_bf16 v[72:75], v[136:139], v[212:215], v[72:75]
	v_mfma_f32_16x16x32_bf16 v[124:127], v[132:135], v[192:195], v[124:127]
	v_mfma_f32_16x16x32_bf16 v[120:123], v[140:143], v[192:195], v[120:123]
	v_mfma_f32_16x16x32_bf16 v[108:111], v[132:135], v[200:203], v[108:111]
	v_mfma_f32_16x16x32_bf16 v[104:107], v[140:143], v[200:203], v[104:107]
	v_mfma_f32_16x16x32_bf16 v[92:95], v[132:135], v[208:211], v[92:95]
	v_mfma_f32_16x16x32_bf16 v[88:91], v[140:143], v[208:211], v[88:91]
	v_mfma_f32_16x16x32_bf16 v[76:79], v[132:135], v[216:219], v[76:79]
	v_mfma_f32_16x16x32_bf16 v[72:75], v[140:143], v[216:219], v[72:75]
	s_setprio 0
	s_setprio 1
	v_mfma_f32_16x16x32_bf16 v[116:119], v[162:165], v[178:181], v[116:119]
	v_mfma_f32_16x16x32_bf16 v[112:115], v[170:173], v[178:181], v[112:115]
	v_mfma_f32_16x16x32_bf16 v[100:103], v[162:165], v[196:199], v[100:103]
	v_mfma_f32_16x16x32_bf16 v[96:99], v[170:173], v[196:199], v[96:99]
	v_mfma_f32_16x16x32_bf16 v[84:87], v[162:165], v[204:207], v[84:87]
	v_mfma_f32_16x16x32_bf16 v[80:83], v[170:173], v[204:207], v[80:83]
	v_mfma_f32_16x16x32_bf16 v[68:71], v[162:165], v[212:215], v[68:71]
	v_mfma_f32_16x16x32_bf16 v[64:67], v[170:173], v[212:215], v[64:67]
	v_mfma_f32_16x16x32_bf16 v[116:119], v[166:169], v[192:195], v[116:119]
	v_mfma_f32_16x16x32_bf16 v[112:115], v[174:177], v[192:195], v[112:115]
	v_mfma_f32_16x16x32_bf16 v[100:103], v[166:169], v[200:203], v[100:103]
	v_mfma_f32_16x16x32_bf16 v[96:99], v[174:177], v[200:203], v[96:99]
	v_mfma_f32_16x16x32_bf16 v[84:87], v[166:169], v[208:211], v[84:87]
	v_mfma_f32_16x16x32_bf16 v[80:83], v[174:177], v[208:211], v[80:83]
	v_mfma_f32_16x16x32_bf16 v[68:71], v[166:169], v[216:219], v[68:71]
	v_mfma_f32_16x16x32_bf16 v[64:67], v[174:177], v[216:219], v[64:67]
	s_barrier
	s_setprio 0
	s_add_i32 s40, s57, s35
	v_lshl_add_u64 v[182:183], v[182:183], 0, s[14:15]
	s_mov_b32 m0, s40
	ds_read_b128 v[178:181], v188 offset:49152
	ds_read_b128 v[192:195], v188 offset:50176
	ds_read_b128 v[196:199], v188 offset:51200
	ds_read_b128 v[200:203], v188 offset:52224
	ds_read_b128 v[204:207], v188 offset:53248
	ds_read_b128 v[208:211], v188 offset:54272
	ds_read_b128 v[212:215], v188 offset:55296
	ds_read_b128 v[216:219], v188 offset:56320
	global_load_lds_dwordx4 v[182:183], off
	s_add_i32 m0, s40, 0x2000
	s_add_u32 s38, s38, 0x80080
	v_lshl_add_u64 v[182:183], v[220:221], 0, s[14:15]
	s_addc_u32 s39, s39, 0
	s_add_i32 s40, s58, s35
	global_load_lds_dwordx4 v[182:183], off
	v_lshl_add_u64 v[182:183], s[38:39], 0, v[148:149]
	s_mov_b32 m0, s40
	s_nop 0
	global_load_lds_dwordx4 v[182:183], off
	v_lshl_add_u64 v[182:183], s[38:39], 0, v[144:145]
	s_add_i32 m0, s40, 0x2000
	s_nop 0
	global_load_lds_dwordx4 v[182:183], off
	v_lshl_add_u64 v[182:183], v[222:223], 0, s[14:15]
	s_mov_b32 m0, s49
	s_nop 0
	global_load_lds_dwordx4 v[182:183], off
	v_lshl_add_u64 v[182:183], v[224:225], 0, s[14:15]
	s_mov_b32 m0, s50
	s_nop 0
	global_load_lds_dwordx4 v[182:183], off
	s_waitcnt vmcnt(8) lgkmcnt(0)
	s_setprio 1
	s_barrier
	v_mfma_f32_16x16x32_bf16 v[60:63], v[128:131], v[178:181], v[60:63]
	v_mfma_f32_16x16x32_bf16 v[56:59], v[136:139], v[178:181], v[56:59]
	v_mfma_f32_16x16x32_bf16 v[44:47], v[128:131], v[196:199], v[44:47]
	v_mfma_f32_16x16x32_bf16 v[40:43], v[136:139], v[196:199], v[40:43]
	v_mfma_f32_16x16x32_bf16 v[28:31], v[128:131], v[204:207], v[28:31]
	v_mfma_f32_16x16x32_bf16 v[24:27], v[136:139], v[204:207], v[24:27]
	v_mfma_f32_16x16x32_bf16 v[12:15], v[128:131], v[212:215], v[12:15]
	v_mfma_f32_16x16x32_bf16 v[8:11], v[136:139], v[212:215], v[8:11]
	v_mfma_f32_16x16x32_bf16 v[60:63], v[132:135], v[192:195], v[60:63]
	v_mfma_f32_16x16x32_bf16 v[56:59], v[140:143], v[192:195], v[56:59]
	v_mfma_f32_16x16x32_bf16 v[44:47], v[132:135], v[200:203], v[44:47]
	v_mfma_f32_16x16x32_bf16 v[40:43], v[140:143], v[200:203], v[40:43]
	v_mfma_f32_16x16x32_bf16 v[28:31], v[132:135], v[208:211], v[28:31]
	v_mfma_f32_16x16x32_bf16 v[24:27], v[140:143], v[208:211], v[24:27]
	v_mfma_f32_16x16x32_bf16 v[12:15], v[132:135], v[216:219], v[12:15]
	v_mfma_f32_16x16x32_bf16 v[8:11], v[140:143], v[216:219], v[8:11]
	s_setprio 0
	s_setprio 1
	v_mfma_f32_16x16x32_bf16 v[52:55], v[162:165], v[178:181], v[52:55]
	v_mfma_f32_16x16x32_bf16 v[48:51], v[170:173], v[178:181], v[48:51]
	v_mfma_f32_16x16x32_bf16 v[36:39], v[162:165], v[196:199], v[36:39]
	v_mfma_f32_16x16x32_bf16 v[32:35], v[170:173], v[196:199], v[32:35]
	s_add_i32 s56, s56, 2
	v_mfma_f32_16x16x32_bf16 v[20:23], v[162:165], v[204:207], v[20:23]
	s_add_u32 s6, s6, 0x100
	v_mfma_f32_16x16x32_bf16 v[16:19], v[170:173], v[204:207], v[16:19]
	s_addc_u32 s7, s7, 0
	v_mfma_f32_16x16x32_bf16 v[4:7], v[162:165], v[212:215], v[4:7]
	s_add_u32 s5, s5, 0x100
	v_mfma_f32_16x16x32_bf16 v[0:3], v[170:173], v[212:215], v[0:3]
	s_addc_u32 s25, s25, 0
	v_mfma_f32_16x16x32_bf16 v[52:55], v[166:169], v[192:195], v[52:55]
	s_cmp_gt_u32 s56, 29
	v_mfma_f32_16x16x32_bf16 v[48:51], v[174:177], v[192:195], v[48:51]
	v_mfma_f32_16x16x32_bf16 v[36:39], v[166:169], v[200:203], v[36:39]
	v_mfma_f32_16x16x32_bf16 v[32:35], v[174:177], v[200:203], v[32:35]
	v_mfma_f32_16x16x32_bf16 v[20:23], v[166:169], v[208:211], v[20:23]
	v_mfma_f32_16x16x32_bf16 v[16:19], v[174:177], v[208:211], v[16:19]
	v_mfma_f32_16x16x32_bf16 v[4:7], v[166:169], v[216:219], v[4:7]
	v_mfma_f32_16x16x32_bf16 v[0:3], v[174:177], v[216:219], v[0:3]
	s_barrier
	s_setprio 0
	s_cbranch_scc0 .LBB0_672
	s_and_b64 vcc, exec, s[18:19]
	s_cbranch_vccz .LBB0_675
	s_barrier
